# rwkv_prep: de-serialized predicated prev-token / v_first loads, pipelined LoRA weight-fragment loads before MFMAs, restructured both value-residual matvec loops (loads up front, double-buffered LDS re
# speedup vs baseline: 1.0408x; 1.0226x over previous
; DEVI void rwkv_prep(const Params& p, int l, unsigned char* smem, int item) {
;     ...
;     for (int i = 0; i < 14; ++i) {
;         const int e = tid + i * NT, t = e / 448, j = e % 448, col = 1536 + j, tok = tok0 + t;
;         lx[i] = P[(size_t)tok * 2048 + col]; lxp[i] = tok > 0 ? P[(size_t)(tok - 1) * 2048 + col] : (bf16_t)0;
;     }
.LBB0_311:
	v_mov_b32_e32 v16, v199
	s_mov_b32 s7, 0x92492493
	s_mov_b64 s[0:1], 0
	v_mul_hi_i32 v0, v16, s7
	v_add_u32_e32 v0, v0, v16
	v_lshrrev_b32_e32 v1, 31, v0
	v_ashrrev_i32_e32 v0, 8, v0
	s_add_u32 s30, s88, s0
	v_add_u32_e32 v27, v0, v1
	s_addc_u32 s31, s89, s1
	s_lshl_b32 s28, s86, 4
	v_mul_i32_i24_e32 v0, 0x1c0, v27
	v_sub_u32_e32 v28, v16, v0
	v_add_u32_e32 v0, s28, v27
	s_add_u32 s38, s30, 0x1c700000
	v_ashrrev_i32_e32 v1, 31, v0
	s_addc_u32 s39, s31, 0
	v_lshlrev_b64 v[2:3], 12, v[0:1]
	v_add_u32_e32 v148, 0x600, v28
	v_lshl_add_u64 v[2:3], s[38:39], 0, v[2:3]
	v_lshl_add_u64 v[2:3], v[148:149], 1, v[2:3]
	global_load_ushort v57, v[2:3], off
	v_cmp_lt_i32_e32 vcc, 0, v0
	v_mov_b32_e32 v55, 0
	v_mov_b32_e32 v58, 0
	v_mov_b32_e32 v220, 0
	s_and_saveexec_b64 s[0:1], vcc
	s_cbranch_execz .LBB0_313
	v_add_u32_e32 v0, -1, v0
	v_mov_b32_e32 v1, v149
	v_lshlrev_b64 v[0:1], 12, v[0:1]
	v_lshl_add_u64 v[0:1], s[38:39], 0, v[0:1]
	v_lshl_add_u64 v[0:1], v[148:149], 1, v[0:1]
	global_load_ushort v220, v[0:1], off
.LBB0_313:
	s_or_b64 exec, exec, s[0:1]
	v_add_u32_e32 v0, 0x200, v16
	v_mul_hi_i32 v1, v0, s7
	v_add_u32_e32 v1, v1, v0
	v_lshrrev_b32_e32 v2, 31, v1
	v_ashrrev_i32_e32 v1, 8, v1
	v_add_u32_e32 v25, v1, v2
	v_mul_i32_i24_e32 v1, 0x1c0, v25
	v_sub_u32_e32 v26, v0, v1
	v_add_u32_e32 v0, s28, v25
	v_ashrrev_i32_e32 v1, 31, v0
	v_lshlrev_b64 v[2:3], 12, v[0:1]
	v_add_u32_e32 v148, 0x600, v26
	v_lshl_add_u64 v[2:3], s[38:39], 0, v[2:3]
	v_lshl_add_u64 v[2:3], v[148:149], 1, v[2:3]
	global_load_ushort v56, v[2:3], off
	v_cmp_lt_i32_e32 vcc, 0, v0
	v_mov_b32_e32 v221, 0
	s_and_saveexec_b64 s[0:1], vcc
	s_movk_i32 s6, 0xc0
	s_cbranch_execz .LBB0_315
	v_add_u32_e32 v0, -1, v0
	v_mov_b32_e32 v1, v149
	v_lshlrev_b64 v[0:1], 12, v[0:1]
	v_lshl_add_u64 v[0:1], s[38:39], 0, v[0:1]
	v_lshl_add_u64 v[0:1], v[148:149], 1, v[0:1]
	global_load_ushort v221, v[0:1], off
.LBB0_315:
	s_or_b64 exec, exec, s[0:1]
	v_add_u32_e32 v0, 0x400, v16
	v_mul_hi_i32 v1, v0, s7
	v_add_u32_e32 v1, v1, v0
	v_lshrrev_b32_e32 v2, 31, v1
	v_ashrrev_i32_e32 v1, 8, v1
	v_add_u32_e32 v23, v1, v2
	v_mul_i32_i24_e32 v1, 0x1c0, v23
	v_sub_u32_e32 v24, v0, v1
	v_add_u32_e32 v0, s28, v23
	v_ashrrev_i32_e32 v1, 31, v0
	v_lshlrev_b64 v[2:3], 12, v[0:1]
	v_add_u32_e32 v148, 0x600, v24
	v_lshl_add_u64 v[2:3], s[38:39], 0, v[2:3]
	v_lshl_add_u64 v[2:3], v[148:149], 1, v[2:3]
	global_load_ushort v53, v[2:3], off
	v_cmp_lt_i32_e32 vcc, 0, v0
	v_mov_b32_e32 v51, 0
	v_mov_b32_e32 v54, 0
	v_mov_b32_e32 v222, 0
	s_and_saveexec_b64 s[0:1], vcc
	s_cbranch_execz .LBB0_317
	v_add_u32_e32 v0, -1, v0
	v_mov_b32_e32 v1, v149
	v_lshlrev_b64 v[0:1], 12, v[0:1]
	v_lshl_add_u64 v[0:1], s[38:39], 0, v[0:1]
	v_lshl_add_u64 v[0:1], v[148:149], 1, v[0:1]
	global_load_ushort v222, v[0:1], off
.LBB0_317:
	s_or_b64 exec, exec, s[0:1]
	v_add_u32_e32 v0, 0x600, v16
	v_mul_hi_i32 v1, v0, s7
	v_add_u32_e32 v1, v1, v0
	v_lshrrev_b32_e32 v2, 31, v1
	v_ashrrev_i32_e32 v1, 8, v1
	v_add_u32_e32 v21, v1, v2
	v_mul_i32_i24_e32 v1, 0x1c0, v21
	v_sub_u32_e32 v22, v0, v1
	v_add_u32_e32 v0, s28, v21
	v_ashrrev_i32_e32 v1, 31, v0
	v_lshlrev_b64 v[2:3], 12, v[0:1]
	v_add_u32_e32 v148, 0x600, v22
	v_lshl_add_u64 v[2:3], s[38:39], 0, v[2:3]
	v_lshl_add_u64 v[2:3], v[148:149], 1, v[2:3]
	global_load_ushort v52, v[2:3], off
	v_cmp_lt_i32_e32 vcc, 0, v0
	v_mov_b32_e32 v223, 0
	s_and_saveexec_b64 s[0:1], vcc
	s_cbranch_execz .LBB0_319
	v_add_u32_e32 v0, -1, v0
	v_mov_b32_e32 v1, v149
	v_lshlrev_b64 v[0:1], 12, v[0:1]
	v_lshl_add_u64 v[0:1], s[38:39], 0, v[0:1]
	v_lshl_add_u64 v[0:1], v[148:149], 1, v[0:1]
	global_load_ushort v223, v[0:1], off
.LBB0_319:
	s_or_b64 exec, exec, s[0:1]
	v_add_u32_e32 v0, 0x800, v16
	v_mul_hi_i32 v1, v0, s7
	v_add_u32_e32 v1, v1, v0
	v_lshrrev_b32_e32 v2, 31, v1
	v_ashrrev_i32_e32 v1, 8, v1
	v_add_u32_e32 v19, v1, v2
	v_mul_i32_i24_e32 v1, 0x1c0, v19
	v_sub_u32_e32 v20, v0, v1
	v_add_u32_e32 v0, s28, v19
	v_ashrrev_i32_e32 v1, 31, v0
	v_lshlrev_b64 v[2:3], 12, v[0:1]
	v_add_u32_e32 v148, 0x600, v20
	v_lshl_add_u64 v[2:3], s[38:39], 0, v[2:3]
	v_lshl_add_u64 v[2:3], v[148:149], 1, v[2:3]
	global_load_ushort v49, v[2:3], off
	v_cmp_lt_i32_e32 vcc, 0, v0
	v_mov_b32_e32 v47, 0
	v_mov_b32_e32 v50, 0
	v_mov_b32_e32 v224, 0
	s_and_saveexec_b64 s[0:1], vcc
	s_cbranch_execz .LBB0_321
	v_add_u32_e32 v0, -1, v0
	v_mov_b32_e32 v1, v149
	v_lshlrev_b64 v[0:1], 12, v[0:1]
	v_lshl_add_u64 v[0:1], s[38:39], 0, v[0:1]
	v_lshl_add_u64 v[0:1], v[148:149], 1, v[0:1]
	global_load_ushort v224, v[0:1], off
.LBB0_321:
	s_or_b64 exec, exec, s[0:1]
	v_add_u32_e32 v0, 0xa00, v16
	v_mul_hi_i32 v1, v0, s7
	v_add_u32_e32 v1, v1, v0
	v_lshrrev_b32_e32 v2, 31, v1
	v_ashrrev_i32_e32 v1, 8, v1
	v_add_u32_e32 v15, v1, v2
	v_mul_i32_i24_e32 v1, 0x1c0, v15
	v_sub_u32_e32 v18, v0, v1
	v_add_u32_e32 v0, s28, v15
	v_ashrrev_i32_e32 v1, 31, v0
	v_lshlrev_b64 v[2:3], 12, v[0:1]
	v_add_u32_e32 v148, 0x600, v18
	v_lshl_add_u64 v[2:3], s[38:39], 0, v[2:3]
	v_lshl_add_u64 v[2:3], v[148:149], 1, v[2:3]
	global_load_ushort v48, v[2:3], off
	v_cmp_lt_i32_e32 vcc, 0, v0
	v_mov_b32_e32 v225, 0
	s_and_saveexec_b64 s[0:1], vcc
	s_cbranch_execz .LBB0_323
	v_add_u32_e32 v0, -1, v0
	v_mov_b32_e32 v1, v149
	v_lshlrev_b64 v[0:1], 12, v[0:1]
	v_lshl_add_u64 v[0:1], s[38:39], 0, v[0:1]
	v_lshl_add_u64 v[0:1], v[148:149], 1, v[0:1]
	global_load_ushort v225, v[0:1], off
; DEVI void rwkv_prep(const Params& p, int l, unsigned char* smem, int item) {
;     ...
;     for (int i = 0; i < 14; ++i) {
;         const int e = tid + i * NT, t = e / 448, j = e % 448, col = 1536 + j, tok = tok0 + t;
;         lx[i] = P[(size_t)tok * 2048 + col]; lxp[i] = tok > 0 ? P[(size_t)(tok - 1) * 2048 + col] : (bf16_t)0;
;     }
.LBB0_323:
	s_or_b64 exec, exec, s[0:1]
	v_add_u32_e32 v0, 0xc00, v16
	v_mul_hi_i32 v1, v0, s7
	v_add_u32_e32 v1, v1, v0
	v_lshrrev_b32_e32 v2, 31, v1
	v_ashrrev_i32_e32 v1, 8, v1
	v_add_u32_e32 v13, v1, v2
	v_mul_i32_i24_e32 v1, 0x1c0, v13
	v_sub_u32_e32 v14, v0, v1
	v_add_u32_e32 v0, s28, v13
	v_ashrrev_i32_e32 v1, 31, v0
	v_lshlrev_b64 v[2:3], 12, v[0:1]
	v_add_u32_e32 v148, 0x600, v14
	v_lshl_add_u64 v[2:3], s[38:39], 0, v[2:3]
	v_lshl_add_u64 v[2:3], v[148:149], 1, v[2:3]
	global_load_ushort v45, v[2:3], off
	v_cmp_lt_i32_e32 vcc, 0, v0
	v_mov_b32_e32 v43, 0
	v_mov_b32_e32 v46, 0
	v_mov_b32_e32 v226, 0
	s_and_saveexec_b64 s[0:1], vcc
	s_cbranch_execz .LBB0_325
	v_add_u32_e32 v0, -1, v0
	v_mov_b32_e32 v1, v149
	v_lshlrev_b64 v[0:1], 12, v[0:1]
	v_lshl_add_u64 v[0:1], s[38:39], 0, v[0:1]
	v_lshl_add_u64 v[0:1], v[148:149], 1, v[0:1]
	global_load_ushort v226, v[0:1], off
.LBB0_325:
	s_or_b64 exec, exec, s[0:1]
	v_add_u32_e32 v0, 0xe00, v16
	v_mul_hi_i32 v1, v0, s7
	v_add_u32_e32 v1, v1, v0
	v_lshrrev_b32_e32 v2, 31, v1
	v_ashrrev_i32_e32 v1, 8, v1
	v_add_u32_e32 v11, v1, v2
	v_mul_i32_i24_e32 v1, 0x1c0, v11
	v_sub_u32_e32 v12, v0, v1
	v_add_u32_e32 v0, s28, v11
	v_ashrrev_i32_e32 v1, 31, v0
	v_lshlrev_b64 v[2:3], 12, v[0:1]
	v_add_u32_e32 v148, 0x600, v12
	v_lshl_add_u64 v[2:3], s[38:39], 0, v[2:3]
	v_lshl_add_u64 v[2:3], v[148:149], 1, v[2:3]
	global_load_ushort v44, v[2:3], off
	v_cmp_lt_i32_e32 vcc, 0, v0
	v_mov_b32_e32 v227, 0
	s_and_saveexec_b64 s[0:1], vcc
	s_cbranch_execz .LBB0_327
	v_add_u32_e32 v0, -1, v0
	v_mov_b32_e32 v1, v149
	v_lshlrev_b64 v[0:1], 12, v[0:1]
	v_lshl_add_u64 v[0:1], s[38:39], 0, v[0:1]
	v_lshl_add_u64 v[0:1], v[148:149], 1, v[0:1]
	global_load_ushort v227, v[0:1], off
.LBB0_327:
	s_or_b64 exec, exec, s[0:1]
	v_add_u32_e32 v0, 0x1000, v16
	v_mul_hi_i32 v1, v0, s7
	v_add_u32_e32 v1, v1, v0
	v_lshrrev_b32_e32 v2, 31, v1
	v_ashrrev_i32_e32 v1, 8, v1
	v_add_u32_e32 v9, v1, v2
	v_mul_i32_i24_e32 v1, 0x1c0, v9
	v_sub_u32_e32 v10, v0, v1
	v_add_u32_e32 v0, s28, v9
	v_ashrrev_i32_e32 v1, 31, v0
	v_lshlrev_b64 v[2:3], 12, v[0:1]
	v_add_u32_e32 v148, 0x600, v10
	v_lshl_add_u64 v[2:3], s[38:39], 0, v[2:3]
	v_lshl_add_u64 v[2:3], v[148:149], 1, v[2:3]
	global_load_ushort v41, v[2:3], off
	v_cmp_lt_i32_e32 vcc, 0, v0
	v_mov_b32_e32 v39, 0
	v_mov_b32_e32 v42, 0
	v_mov_b32_e32 v228, 0
	s_and_saveexec_b64 s[0:1], vcc
	s_cbranch_execz .LBB0_329
	v_add_u32_e32 v0, -1, v0
	v_mov_b32_e32 v1, v149
	v_lshlrev_b64 v[0:1], 12, v[0:1]
	v_lshl_add_u64 v[0:1], s[38:39], 0, v[0:1]
	v_lshl_add_u64 v[0:1], v[148:149], 1, v[0:1]
	global_load_ushort v228, v[0:1], off
.LBB0_329:
	s_or_b64 exec, exec, s[0:1]
	v_add_u32_e32 v0, 0x1200, v16
	v_mul_hi_i32 v1, v0, s7
	v_add_u32_e32 v1, v1, v0
	v_lshrrev_b32_e32 v2, 31, v1
	v_ashrrev_i32_e32 v1, 8, v1
	v_add_u32_e32 v7, v1, v2
	v_mul_i32_i24_e32 v1, 0x1c0, v7
	v_sub_u32_e32 v8, v0, v1
	v_add_u32_e32 v0, s28, v7
	v_ashrrev_i32_e32 v1, 31, v0
	v_lshlrev_b64 v[2:3], 12, v[0:1]
	v_add_u32_e32 v148, 0x600, v8
	v_lshl_add_u64 v[2:3], s[38:39], 0, v[2:3]
	v_lshl_add_u64 v[2:3], v[148:149], 1, v[2:3]
	global_load_ushort v40, v[2:3], off
	v_cmp_lt_i32_e32 vcc, 0, v0
	v_mov_b32_e32 v229, 0
	s_and_saveexec_b64 s[0:1], vcc
	s_cbranch_execz .LBB0_331
	v_add_u32_e32 v0, -1, v0
	v_mov_b32_e32 v1, v149
	v_lshlrev_b64 v[0:1], 12, v[0:1]
	v_lshl_add_u64 v[0:1], s[38:39], 0, v[0:1]
	v_lshl_add_u64 v[0:1], v[148:149], 1, v[0:1]
	global_load_ushort v229, v[0:1], off
.LBB0_331:
	s_or_b64 exec, exec, s[0:1]
	v_add_u32_e32 v0, 0x1400, v16
	v_mul_hi_i32 v1, v0, s7
	v_add_u32_e32 v1, v1, v0
	v_lshrrev_b32_e32 v2, 31, v1
	v_ashrrev_i32_e32 v1, 8, v1
	v_add_u32_e32 v5, v1, v2
	v_mul_i32_i24_e32 v1, 0x1c0, v5
	v_sub_u32_e32 v6, v0, v1
	v_add_u32_e32 v0, s28, v5
	v_ashrrev_i32_e32 v1, 31, v0
	v_lshlrev_b64 v[2:3], 12, v[0:1]
	v_add_u32_e32 v148, 0x600, v6
	v_lshl_add_u64 v[2:3], s[38:39], 0, v[2:3]
	v_lshl_add_u64 v[2:3], v[148:149], 1, v[2:3]
	global_load_ushort v37, v[2:3], off
	v_cmp_lt_i32_e32 vcc, 0, v0
	v_mov_b32_e32 v35, 0
	v_mov_b32_e32 v38, 0
	v_mov_b32_e32 v230, 0
	s_and_saveexec_b64 s[0:1], vcc
	s_cbranch_execz .LBB0_333
	v_add_u32_e32 v0, -1, v0
	v_mov_b32_e32 v1, v149
	v_lshlrev_b64 v[0:1], 12, v[0:1]
	v_lshl_add_u64 v[0:1], s[38:39], 0, v[0:1]
	v_lshl_add_u64 v[0:1], v[148:149], 1, v[0:1]
	global_load_ushort v230, v[0:1], off
; DEVI float bf2f(bf16_t b) { return __uint_as_float(((unsigned)b) << 16); }
; DEVI void rwkv_prep(const Params& p, int l, unsigned char* smem, int item) {
;     ...
;     for (int i = 0; i < 14; ++i) {
;         const int e = tid + i * NT, t = e / 448, j = e % 448, col = 1536 + j, tok = tok0 + t;
;         lx[i] = P[(size_t)tok * 2048 + col]; lxp[i] = tok > 0 ? P[(size_t)(tok - 1) * 2048 + col] : (bf16_t)0;
;     }
; #pragma unroll
;     for (int i = 0; i < 14; ++i) {
;         const int e = tid + i * NT;
;         const int t = e / 448, j = e % 448, col = 1536 + j;
;         const float x = bf2f(lx[i]);
;         const float xp = bf2f(lxp[i]);
;         const float xs = x + (xp - x) * mu[col];
;         float v;
;         if (j < 96) { const float e2 = __expf(2.0f * xs); v = 1.0f - 2.0f * __builtin_amdgcn_rcpf(e2 + 1.0f); }
.LBB0_333:
	s_or_b64 exec, exec, s[0:1]
	v_add_u32_e32 v0, 0x1600, v16
	v_mul_hi_i32 v1, v0, s7
	v_add_u32_e32 v1, v1, v0
	v_lshrrev_b32_e32 v2, 31, v1
	v_ashrrev_i32_e32 v1, 8, v1
	v_add_u32_e32 v3, v1, v2
	v_mul_i32_i24_e32 v1, 0x1c0, v3
	v_sub_u32_e32 v4, v0, v1
	v_add_u32_e32 v0, s28, v3
	v_ashrrev_i32_e32 v1, 31, v0
	v_lshlrev_b64 v[30:31], 12, v[0:1]
	v_add_u32_e32 v148, 0x600, v4
	v_lshl_add_u64 v[30:31], s[38:39], 0, v[30:31]
	v_lshl_add_u64 v[30:31], v[148:149], 1, v[30:31]
	global_load_ushort v36, v[30:31], off
	v_cmp_lt_i32_e32 vcc, 0, v0
	v_mov_b32_e32 v231, 0
	s_and_saveexec_b64 s[0:1], vcc
	s_cbranch_execz .LBB0_335
	v_add_u32_e32 v0, -1, v0
	v_mov_b32_e32 v1, v149
	v_lshlrev_b64 v[0:1], 12, v[0:1]
	v_lshl_add_u64 v[0:1], s[38:39], 0, v[0:1]
	v_lshl_add_u64 v[0:1], v[148:149], 1, v[0:1]
	global_load_ushort v231, v[0:1], off
.LBB0_335:
	s_or_b64 exec, exec, s[0:1]
	v_add_u32_e32 v0, 0x1800, v16
	v_mul_hi_i32 v1, v0, s7
	v_add_u32_e32 v1, v1, v0
	v_lshrrev_b32_e32 v2, 31, v1
	v_ashrrev_i32_e32 v1, 8, v1
	v_add_u32_e32 v32, v1, v2
	v_mul_i32_i24_e32 v1, 0x1c0, v32
	v_sub_u32_e32 v2, v0, v1
	v_add_u32_e32 v0, s28, v32
	v_ashrrev_i32_e32 v1, 31, v0
	v_lshlrev_b64 v[30:31], 12, v[0:1]
	v_add_u32_e32 v148, 0x600, v2
	v_lshl_add_u64 v[30:31], s[38:39], 0, v[30:31]
	v_lshl_add_u64 v[30:31], v[148:149], 1, v[30:31]
	global_load_ushort v33, v[30:31], off
	v_cmp_lt_i32_e32 vcc, 0, v0
	v_mov_b32_e32 v1, 0
	v_mov_b32_e32 v34, 0
	v_mov_b32_e32 v232, 0
	s_and_saveexec_b64 s[0:1], vcc
	s_cbranch_execz .LBB0_337
	v_add_u32_e32 v30, -1, v0
	v_mov_b32_e32 v31, v149
	v_lshlrev_b64 v[30:31], 12, v[30:31]
	v_lshl_add_u64 v[30:31], s[38:39], 0, v[30:31]
	v_lshl_add_u64 v[30:31], v[148:149], 1, v[30:31]
	global_load_ushort v232, v[30:31], off
.LBB0_337:
	s_or_b64 exec, exec, s[0:1]
	v_add_u32_e32 v0, 0x1a00, v16
	v_mul_hi_i32 v17, v0, s7
	v_add_u32_e32 v17, v17, v0
	v_lshrrev_b32_e32 v29, 31, v17
	v_ashrrev_i32_e32 v17, 8, v17
	v_add_u32_e32 v17, v17, v29
	v_add_u32_e32 v30, s28, v17
	v_mul_i32_i24_e32 v29, 0x1c0, v17
	v_ashrrev_i32_e32 v31, 31, v30
	v_sub_u32_e32 v0, v0, v29
	v_lshlrev_b64 v[60:61], 12, v[30:31]
	v_add_u32_e32 v148, 0x600, v0
	v_lshl_add_u64 v[60:61], s[38:39], 0, v[60:61]
	v_lshl_add_u64 v[60:61], v[148:149], 1, v[60:61]
	global_load_ushort v31, v[60:61], off
	v_cmp_lt_i32_e32 vcc, 0, v30
	v_mov_b32_e32 v233, 0
	s_and_saveexec_b64 s[0:1], vcc
	s_cbranch_execz .LBB0_339
	v_add_u32_e32 v60, -1, v30
	v_mov_b32_e32 v61, v149
	v_lshlrev_b64 v[60:61], 12, v[60:61]
	v_lshl_add_u64 v[60:61], s[38:39], 0, v[60:61]
	v_lshl_add_u64 v[60:61], v[148:149], 1, v[60:61]
	global_load_ushort v233, v[60:61], off
.LBB0_339:
	s_or_b64 exec, exec, s[0:1]
	s_waitcnt vmcnt(0)
	v_lshlrev_b32_e32 v58, 16, v220
	v_lshlrev_b32_e32 v55, 16, v221
	v_lshlrev_b32_e32 v54, 16, v222
	v_lshlrev_b32_e32 v51, 16, v223
	v_lshlrev_b32_e32 v50, 16, v224
	v_lshlrev_b32_e32 v47, 16, v225
	v_lshlrev_b32_e32 v46, 16, v226
	v_lshlrev_b32_e32 v43, 16, v227
	v_lshlrev_b32_e32 v42, 16, v228
	v_lshlrev_b32_e32 v39, 16, v229
	v_lshlrev_b32_e32 v38, 16, v230
	v_lshlrev_b32_e32 v35, 16, v231
	v_lshlrev_b32_e32 v34, 16, v232
	v_lshlrev_b32_e32 v1, 16, v233
	v_ashrrev_i32_e32 v29, 31, v28
	v_lshl_add_u64 v[60:61], v[28:29], 2, s[92:93]
	v_add_co_u32_e32 v60, vcc, 0x1000, v60
	s_waitcnt vmcnt(13)
	v_lshlrev_b32_e32 v29, 16, v57
	v_addc_co_u32_e32 v61, vcc, 0, v61, vcc
	global_load_dword v30, v[60:61], off offset:2048
	v_sub_f32_e32 v57, v58, v29
	v_cmp_lt_i32_e32 vcc, s77, v28
	s_waitcnt vmcnt(0)
	v_fmac_f32_e32 v29, v57, v30
	s_and_saveexec_b64 s[0:1], vcc
	s_xor_b64 s[0:1], exec, s[0:1]
	s_cbranch_execz .LBB0_341
	v_mul_f32_e32 v30, 0xbfb8aa3b, v29
	v_exp_f32_e32 v30, v30
	v_cmp_gt_u32_e32 vcc, s6, v28
	v_add_f32_e32 v30, 1.0, v30
	v_rcp_f32_e32 v30, v30
	s_nop 0
	v_cndmask_b32_e32 v30, v30, v29, vcc

; DEVI void rwkv_prep(const Params& p, int l, unsigned char* smem, int item) {
;     ...
;     bf16_t xv[17];
;     xv[0] = tok0 > 0 ? P[(size_t)(tok0 - 1) * 2048 + 1024 + c] : (bf16_t)0;
; #pragma unroll
;     for (int t = 0; t < 16; ++t) xv[t + 1] = P[(size_t)(tok0 + t) * 2048 + 1024 + c];
;     __syncthreads();
;     {
;         const int wid = tid >> 6, lane = tid & 63, li = lane & 15, g = lane >> 4;
;         const bf16_t* WT = (const bf16_t*)(ws_ + OFF_LORA);
; #pragma unroll
;         for (int lo = 0; lo < 3; ++lo) {
;             const int kb = lo == 0 ? 0 : (lo == 1 ? 96 : 192), nks = lo == 2 ? 8 : 3;
;             f32x4 acc[4];
; #pragma unroll
;             for (int q = 0; q < 4; ++q) acc[q] = (f32x4){0.f, 0.f, 0.f, 0.f};
;             for (int ks = 0; ks < nks; ++ks) {
;                 const bf16x8 af = *(const bf16x8*)(sX + li * 456 + kb + ks * 32 + g * 8);
; #pragma unroll
;                 for (int q = 0; q < 4; ++q) {
;                     const bf16x8 bfr = *(const bf16x8*)(WT + (size_t)((wid * 4 + q) * 16 + li) * 448 + kb + ks * 32 + g * 8);
;                     acc[q] = __builtin_amdgcn_mfma_f32_16x16x32_bf16(af, bfr, acc[q], 0, 0, 0);
;                 }
;             }
.LBB0_398:
	s_ashr_i32 s29, s28, 31
	s_lshl_b64 s[0:1], s[28:29], 12
	s_add_u32 s0, s38, s0
	s_addc_u32 s1, s39, s1
	s_or_b32 s88, s28, 1
	v_lshlrev_b64 v[4:5], 1, v[16:17]
	s_ashr_i32 s89, s88, 31
	v_lshl_add_u64 v[62:63], s[0:1], 0, v[4:5]
	s_lshl_b64 s[0:1], s[88:89], 12
	s_add_u32 s0, s38, s0
	s_addc_u32 s1, s39, s1
	s_or_b32 s82, s28, 2
	s_ashr_i32 s83, s82, 31
	v_lshl_add_u64 v[60:61], s[0:1], 0, v[4:5]
	s_lshl_b64 s[0:1], s[82:83], 12
	s_add_u32 s0, s38, s0
	s_addc_u32 s1, s39, s1
	s_or_b32 s96, s28, 3
	s_ashr_i32 s97, s96, 31
	v_lshl_add_u64 v[58:59], s[0:1], 0, v[4:5]
	s_lshl_b64 s[0:1], s[96:97], 12
	s_add_u32 s0, s38, s0
	s_addc_u32 s1, s39, s1
	s_or_b32 s94, s28, 4
	s_ashr_i32 s95, s94, 31
	v_lshl_add_u64 v[56:57], s[0:1], 0, v[4:5]
	s_lshl_b64 s[0:1], s[94:95], 12
	s_add_u32 s0, s38, s0
	s_addc_u32 s1, s39, s1
	s_or_b32 s50, s28, 5
	s_ashr_i32 s51, s50, 31
	v_lshl_add_u64 v[54:55], s[0:1], 0, v[4:5]
	s_lshl_b64 s[0:1], s[50:51], 12
	s_add_u32 s0, s38, s0
	s_addc_u32 s1, s39, s1
	s_or_b32 s48, s28, 6
	s_ashr_i32 s49, s48, 31
	v_lshl_add_u64 v[52:53], s[0:1], 0, v[4:5]
	s_lshl_b64 s[0:1], s[48:49], 12
	s_add_u32 s0, s38, s0
	s_addc_u32 s1, s39, s1
	s_or_b32 s46, s28, 7
	s_ashr_i32 s47, s46, 31
	v_lshl_add_u64 v[50:51], s[0:1], 0, v[4:5]
	s_lshl_b64 s[0:1], s[46:47], 12
	s_add_u32 s0, s38, s0
	s_addc_u32 s1, s39, s1
	s_or_b32 s44, s28, 8
	s_ashr_i32 s45, s44, 31
	v_lshl_add_u64 v[48:49], s[0:1], 0, v[4:5]
	s_lshl_b64 s[0:1], s[44:45], 12
	s_add_u32 s0, s38, s0
	s_addc_u32 s1, s39, s1
	s_or_b32 s42, s28, 9
	s_ashr_i32 s43, s42, 31
	v_lshl_add_u64 v[46:47], s[0:1], 0, v[4:5]
	s_lshl_b64 s[0:1], s[42:43], 12
	s_add_u32 s0, s38, s0
	s_addc_u32 s1, s39, s1
	s_or_b32 s40, s28, 10
	s_ashr_i32 s41, s40, 31
	v_lshl_add_u64 v[42:43], s[0:1], 0, v[4:5]
	s_lshl_b64 s[0:1], s[40:41], 12
	s_add_u32 s0, s38, s0
	s_addc_u32 s1, s39, s1
	s_or_b32 s36, s28, 11
	s_ashr_i32 s37, s36, 31
	v_lshl_add_u64 v[40:41], s[0:1], 0, v[4:5]
	s_lshl_b64 s[0:1], s[36:37], 12
	s_add_u32 s0, s38, s0
	s_addc_u32 s1, s39, s1
	s_or_b32 s34, s28, 12
	s_ashr_i32 s35, s34, 31
	v_lshl_add_u64 v[38:39], s[0:1], 0, v[4:5]
	s_lshl_b64 s[0:1], s[34:35], 12
	s_add_u32 s0, s38, s0
	s_addc_u32 s1, s39, s1
	s_or_b32 s26, s28, 13
	s_ashr_i32 s27, s26, 31
	v_lshl_add_u64 v[36:37], s[0:1], 0, v[4:5]
	s_lshl_b64 s[0:1], s[26:27], 12
	s_add_u32 s0, s38, s0
	s_addc_u32 s1, s39, s1
	s_or_b32 s24, s28, 14
	s_ashr_i32 s25, s24, 31
	v_lshl_add_u64 v[34:35], s[0:1], 0, v[4:5]
	s_lshl_b64 s[0:1], s[24:25], 12
	s_add_u32 s0, s38, s0
	s_addc_u32 s1, s39, s1
	s_or_b32 s78, s28, 15
	s_ashr_i32 s79, s78, 31
	v_lshl_add_u64 v[32:33], s[0:1], 0, v[4:5]
	s_lshl_b64 s[0:1], s[78:79], 12
	s_add_u32 s0, s38, s0
	s_addc_u32 s1, s39, s1
	v_and_b32_e32 v6, 15, v16
	v_lshl_add_u64 v[30:31], s[0:1], 0, v[4:5]
	v_mul_u32_u24_e32 v4, 0x390, v6
	v_and_b32_e32 v148, 48, v16
	v_add3_u32 v20, 0, v4, v148
	v_lshl_add_u64 v[4:5], s[30:31], 0, v[148:149]
	s_mov_b64 s[0:1], 0x3a1f8000
	v_lshl_add_u64 v[44:45], v[4:5], 0, s[0:1]
	v_lshlrev_b32_e32 v4, 9, v16
	v_and_b32_e32 v21, 0xffffffcf, v16
	v_and_b32_e32 v18, 0x6000, v4
	v_and_b32_e32 v4, 0x3fffffc0, v16
	s_movk_i32 s2, 0x380
	v_lshlrev_b32_e32 v4, 2, v4
	v_lshlrev_b32_e32 v5, 2, v6
	v_mad_i64_i32 v[10:11], s[0:1], v21, s2, v[44:45]
	global_load_ushort v3, v[62:63], off offset:2048
	global_load_ushort v110, v[60:61], off offset:2048
	global_load_ushort v108, v[58:59], off offset:2048
	global_load_ushort v109, v[56:57], off offset:2048
	global_load_ushort v106, v[54:55], off offset:2048
	global_load_ushort v107, v[52:53], off offset:2048
	global_load_ushort v77, v[50:51], off offset:2048
	global_load_ushort v105, v[48:49], off offset:2048
	global_load_ushort v75, v[46:47], off offset:2048
	global_load_ushort v76, v[42:43], off offset:2048
	global_load_ushort v15, v[40:41], off offset:2048
	global_load_ushort v74, v[38:39], off offset:2048
	global_load_ushort v13, v[36:37], off offset:2048
	global_load_ushort v14, v[34:35], off offset:2048
	global_load_ushort v1, v[30:31], off offset:2048
	global_load_ushort v12, v[32:33], off offset:2048
	s_waitcnt lgkmcnt(0)
	s_barrier
	v_add3_u32 v72, 0, v4, v5
	global_load_dwordx4 v[220:223], v[10:11], off
	ds_read_b128 v[22:25], v20
	v_add_u32_e32 v19, 0x4000, v72
	s_waitcnt lgkmcnt(0)
	s_waitcnt vmcnt(0)
	v_mfma_f32_16x16x32_bf16 v[26:29], v[22:25], v[220:223], 0
	v_or_b32_e32 v4, 16, v21
	v_mad_i64_i32 v[8:9], s[0:1], v4, s2, v[44:45]
	global_load_dwordx4 v[224:227], v[8:9], off
	global_load_dwordx4 v[228:231], v[10:11], off offset:64
	s_nop 0
	s_waitcnt vmcnt(1)
	v_mfma_f32_16x16x32_bf16 v[64:67], v[22:25], v[224:227], 0
	v_or_b32_e32 v4, 32, v21
	v_mad_i64_i32 v[6:7], s[0:1], v4, s2, v[44:45]
	v_or_b32_e32 v4, 48, v16
	v_mad_i64_i32 v[4:5], s[0:1], v4, s2, v[44:45]
	global_load_dwordx4 v[232:235], v[6:7], off
	global_load_dwordx4 v[236:239], v[4:5], off
	global_load_dwordx4 v[240:243], v[8:9], off offset:64
	global_load_dwordx4 v[244:247], v[6:7], off offset:64
	global_load_dwordx4 v[248:251], v[4:5], off offset:64
	global_load_dwordx4 v[220:223], v[10:11], off offset:128
	global_load_dwordx4 v[224:227], v[8:9], off offset:128
	s_nop 0
	v_add_u32_e32 v44, v72, v18
	v_add_u32_e32 v45, 0xd000, v44
	v_add_u32_e32 v21, 0x40c0, v72
	v_readlane_b32 s0, v253, 50
	v_readlane_b32 s1, v253, 51
	s_andn2_b64 vcc, exec, s[0:1]
	s_nop 0
	s_waitcnt vmcnt(6)
	v_mfma_f32_16x16x32_bf16 v[68:71], v[22:25], v[232:235], 0
	s_nop 0
	s_waitcnt vmcnt(5)
	v_mfma_f32_16x16x32_bf16 v[22:25], v[22:25], v[236:239], 0
	ds_read_b128 v[80:83], v20 offset:64
	s_waitcnt lgkmcnt(0)
	s_waitcnt vmcnt(7)
; DEVI void rwkv_prep(const Params& p, int l, unsigned char* smem, int item) {
;     ...
; #pragma unroll
;         for (int lo = 0; lo < 3; ++lo) {
;             const int kb = lo == 0 ? 0 : (lo == 1 ? 96 : 192), nks = lo == 2 ? 8 : 3;
;             f32x4 acc[4];
; #pragma unroll
;             for (int q = 0; q < 4; ++q) acc[q] = (f32x4){0.f, 0.f, 0.f, 0.f};
;             for (int ks = 0; ks < nks; ++ks) {
;                 const bf16x8 af = *(const bf16x8*)(sX + li * 456 + kb + ks * 32 + g * 8);
; #pragma unroll
;                 for (int q = 0; q < 4; ++q) {
;                     const bf16x8 bfr = *(const bf16x8*)(WT + (size_t)((wid * 4 + q) * 16 + li) * 448 + kb + ks * 32 + g * 8);
;                     acc[q] = __builtin_amdgcn_mfma_f32_16x16x32_bf16(af, bfr, acc[q], 0, 0, 0);
;                 }
;             }
; #pragma unroll
;             for (int q = 0; q < 4; ++q)
; #pragma unroll
;                 for (int r = 0; r < 4; ++r) sAcc[(lo * 16 + 4 * g + r) * 512 + (wid * 4 + q) * 16 + li] = acc[q][r];
	v_mfma_f32_16x16x32_bf16 v[26:29], v[80:83], v[228:231], v[26:29]
	global_load_dwordx4 v[228:231], v[6:7], off offset:128
	global_load_dwordx4 v[232:235], v[4:5], off offset:128
	global_load_dwordx4 v[236:239], v[10:11], off offset:192
	s_nop 0
	s_waitcnt vmcnt(7)
	v_mfma_f32_16x16x32_bf16 v[64:67], v[80:83], v[240:243], v[64:67]
	global_load_dwordx4 v[240:243], v[8:9], off offset:192
	s_nop 0
	s_waitcnt vmcnt(7)
	v_mfma_f32_16x16x32_bf16 v[68:71], v[80:83], v[244:247], v[68:71]
	global_load_dwordx4 v[244:247], v[6:7], off offset:192
	s_nop 0
	s_waitcnt vmcnt(7)
	v_mfma_f32_16x16x32_bf16 v[22:25], v[80:83], v[248:251], v[22:25]
	global_load_dwordx4 v[248:251], v[4:5], off offset:192
	ds_read_b128 v[80:83], v20 offset:128
	s_waitcnt lgkmcnt(0)
	s_waitcnt vmcnt(7)
	v_mfma_f32_16x16x32_bf16 v[26:29], v[80:83], v[220:223], v[26:29]
	global_load_dwordx4 v[220:223], v[10:11], off offset:256
	s_nop 0
	s_waitcnt vmcnt(7)
	v_mfma_f32_16x16x32_bf16 v[64:67], v[80:83], v[224:227], v[64:67]
	global_load_dwordx4 v[224:227], v[8:9], off offset:256
	s_nop 0
	s_waitcnt vmcnt(7)
	v_mfma_f32_16x16x32_bf16 v[68:71], v[80:83], v[228:231], v[68:71]
	global_load_dwordx4 v[228:231], v[6:7], off offset:256
	s_nop 0
	s_waitcnt vmcnt(7)
	v_mfma_f32_16x16x32_bf16 v[80:83], v[80:83], v[232:235], v[22:25]
	s_nop 2
	v_add_u32_e32 v24, 0x4000, v44
	v_add_u32_e32 v25, 0x4800, v44
	ds_write2_b32 v24, v26, v64 offset1:16
	ds_write2_b32 v25, v27, v65 offset1:16
	v_add_u32_e32 v26, 0x5000, v44
	v_add_u32_e32 v27, 0x5800, v44
	ds_write2_b32 v26, v28, v66 offset1:16
	ds_write2_b32 v27, v29, v67 offset1:16
	ds_write2_b32 v24, v68, v80 offset0:32 offset1:48
	ds_write2_b32 v25, v69, v81 offset0:32 offset1:48
	ds_write2_b32 v26, v70, v82 offset0:32 offset1:48
	ds_write2_b32 v27, v71, v83 offset0:32 offset1:48
	global_load_dwordx4 v[232:235], v[4:5], off offset:256
	s_nop 0
	s_nop 0
	s_nop 0
	s_nop 0
	ds_read_b128 v[24:27], v20 offset:192
	v_add_u32_e32 v28, 0xc000, v44
	v_add_u32_e32 v29, 0xc800, v44
	v_add_u32_e32 v44, 0xd800, v44
	s_waitcnt lgkmcnt(0)
	s_waitcnt vmcnt(7)
	v_mfma_f32_16x16x32_bf16 v[64:67], v[24:27], v[236:239], 0
	global_load_dwordx4 v[236:239], v[10:11], off offset:320
	v_add_u32_e32 v22, 0x4040, v72
	v_add_u32_e32 v23, 0x4080, v72
	s_nop 0
	s_waitcnt vmcnt(7)
	v_mfma_f32_16x16x32_bf16 v[68:71], v[24:27], v[240:243], 0
	global_load_dwordx4 v[240:243], v[8:9], off offset:320
	s_nop 0
	s_waitcnt vmcnt(7)
	v_mfma_f32_16x16x32_bf16 v[80:83], v[24:27], v[244:247], 0
	global_load_dwordx4 v[244:247], v[6:7], off offset:320
	s_nop 0
	s_waitcnt vmcnt(7)
	v_mfma_f32_16x16x32_bf16 v[24:27], v[24:27], v[248:251], 0
	global_load_dwordx4 v[248:251], v[4:5], off offset:320
	ds_read_b128 v[84:87], v20 offset:256
	s_waitcnt lgkmcnt(0)
	s_waitcnt vmcnt(7)
	v_mfma_f32_16x16x32_bf16 v[64:67], v[84:87], v[220:223], v[64:67]
	global_load_dwordx4 v[220:223], v[10:11], off offset:384
	s_nop 0
	s_waitcnt vmcnt(7)
	v_mfma_f32_16x16x32_bf16 v[68:71], v[84:87], v[224:227], v[68:71]
	global_load_dwordx4 v[224:227], v[8:9], off offset:384
	s_nop 0
	s_waitcnt vmcnt(7)
	v_mfma_f32_16x16x32_bf16 v[80:83], v[84:87], v[228:231], v[80:83]
	global_load_dwordx4 v[228:231], v[6:7], off offset:384
	s_nop 0
	s_waitcnt vmcnt(7)
	v_mfma_f32_16x16x32_bf16 v[24:27], v[84:87], v[232:235], v[24:27]
	global_load_dwordx4 v[232:235], v[4:5], off offset:384
	ds_read_b128 v[84:87], v20 offset:320
	s_waitcnt lgkmcnt(0)
	s_waitcnt vmcnt(7)
	v_mfma_f32_16x16x32_bf16 v[64:67], v[84:87], v[236:239], v[64:67]
	global_load_dwordx4 v[236:239], v[10:11], off offset:448
	s_nop 0
	s_waitcnt vmcnt(7)
	v_mfma_f32_16x16x32_bf16 v[68:71], v[84:87], v[240:243], v[68:71]
	global_load_dwordx4 v[240:243], v[8:9], off offset:448
	s_nop 6
	ds_write2_b32 v28, v64, v68 offset1:16
	s_nop 0
	s_waitcnt vmcnt(7)
	v_mfma_f32_16x16x32_bf16 v[80:83], v[84:87], v[244:247], v[80:83]
	global_load_dwordx4 v[244:247], v[6:7], off offset:448
	ds_write2_b32 v29, v65, v69 offset1:16
	ds_write2_b32 v45, v66, v70 offset1:16
	s_nop 0
	s_waitcnt vmcnt(7)
	v_mfma_f32_16x16x32_bf16 v[24:27], v[84:87], v[248:251], v[24:27]
	ds_write2_b32 v44, v67, v71 offset1:16
	s_nop 6
	ds_write2_b32 v28, v80, v24 offset0:32 offset1:48
	ds_write2_b32 v29, v81, v25 offset0:32 offset1:48
	ds_write2_b32 v45, v82, v26 offset0:32 offset1:48
	ds_write2_b32 v44, v83, v27 offset0:32 offset1:48
	global_load_dwordx4 v[248:251], v[4:5], off offset:448
	s_nop 0
	s_nop 0
	s_nop 0
	s_nop 0
	ds_read_b128 v[24:27], v20 offset:384
	s_waitcnt lgkmcnt(0)
	s_waitcnt vmcnt(7)
	v_mfma_f32_16x16x32_bf16 v[64:67], v[24:27], v[220:223], 0
	global_load_dwordx4 v[220:223], v[10:11], off offset:512
	s_nop 0
	s_waitcnt vmcnt(7)
	v_mfma_f32_16x16x32_bf16 v[68:71], v[24:27], v[224:227], 0
	global_load_dwordx4 v[224:227], v[8:9], off offset:512
	s_nop 0
	s_waitcnt vmcnt(7)
	v_mfma_f32_16x16x32_bf16 v[80:83], v[24:27], v[228:231], 0
	global_load_dwordx4 v[228:231], v[6:7], off offset:512
	s_nop 0
	s_waitcnt vmcnt(7)
	v_mfma_f32_16x16x32_bf16 v[24:27], v[24:27], v[232:235], 0
	global_load_dwordx4 v[232:235], v[4:5], off offset:512
	ds_read_b128 v[84:87], v20 offset:448
	s_waitcnt lgkmcnt(0)
	s_waitcnt vmcnt(7)
	v_mfma_f32_16x16x32_bf16 v[64:67], v[84:87], v[236:239], v[64:67]
	global_load_dwordx4 v[236:239], v[10:11], off offset:576
	s_nop 0
	s_waitcnt vmcnt(7)
	v_mfma_f32_16x16x32_bf16 v[68:71], v[84:87], v[240:243], v[68:71]
	global_load_dwordx4 v[240:243], v[8:9], off offset:576
	s_nop 0
	s_waitcnt vmcnt(7)
	v_mfma_f32_16x16x32_bf16 v[80:83], v[84:87], v[244:247], v[80:83]
	global_load_dwordx4 v[244:247], v[6:7], off offset:576
	s_nop 0
	s_waitcnt vmcnt(7)
; DEVI void rwkv_prep(const Params& p, int l, unsigned char* smem, int item) {
;     ...
; #pragma unroll
;         for (int lo = 0; lo < 3; ++lo) {
;             const int kb = lo == 0 ? 0 : (lo == 1 ? 96 : 192), nks = lo == 2 ? 8 : 3;
;             f32x4 acc[4];
; #pragma unroll
;             for (int q = 0; q < 4; ++q) acc[q] = (f32x4){0.f, 0.f, 0.f, 0.f};
;             for (int ks = 0; ks < nks; ++ks) {
;                 const bf16x8 af = *(const bf16x8*)(sX + li * 456 + kb + ks * 32 + g * 8);
; #pragma unroll
;                 for (int q = 0; q < 4; ++q) {
;                     const bf16x8 bfr = *(const bf16x8*)(WT + (size_t)((wid * 4 + q) * 16 + li) * 448 + kb + ks * 32 + g * 8);
;                     acc[q] = __builtin_amdgcn_mfma_f32_16x16x32_bf16(af, bfr, acc[q], 0, 0, 0);
;                 }
;             }
; #pragma unroll
;             for (int q = 0; q < 4; ++q)
; #pragma unroll
;                 for (int r = 0; r < 4; ++r) sAcc[(lo * 16 + 4 * g + r) * 512 + (wid * 4 + q) * 16 + li] = acc[q][r];
;         }
;     }
;     __syncthreads();
	v_mfma_f32_16x16x32_bf16 v[24:27], v[84:87], v[248:251], v[24:27]
	global_load_dwordx4 v[248:251], v[4:5], off offset:576
	ds_read_b128 v[84:87], v20 offset:512
	s_waitcnt lgkmcnt(0)
	s_waitcnt vmcnt(7)
	v_mfma_f32_16x16x32_bf16 v[64:67], v[84:87], v[220:223], v[64:67]
	global_load_dwordx4 v[220:223], v[10:11], off offset:640
	s_nop 0
	s_waitcnt vmcnt(7)
	v_mfma_f32_16x16x32_bf16 v[68:71], v[84:87], v[224:227], v[68:71]
	global_load_dwordx4 v[224:227], v[8:9], off offset:640
	s_nop 0
	s_waitcnt vmcnt(7)
	v_mfma_f32_16x16x32_bf16 v[80:83], v[84:87], v[228:231], v[80:83]
	global_load_dwordx4 v[228:231], v[6:7], off offset:640
	s_nop 0
	s_waitcnt vmcnt(7)
	v_mfma_f32_16x16x32_bf16 v[24:27], v[84:87], v[232:235], v[24:27]
	global_load_dwordx4 v[232:235], v[4:5], off offset:640
	ds_read_b128 v[84:87], v20 offset:576
	s_waitcnt lgkmcnt(0)
	s_waitcnt vmcnt(7)
	v_mfma_f32_16x16x32_bf16 v[64:67], v[84:87], v[236:239], v[64:67]
	global_load_dwordx4 v[236:239], v[10:11], off offset:704
	s_nop 0
	s_waitcnt vmcnt(7)
	v_mfma_f32_16x16x32_bf16 v[68:71], v[84:87], v[240:243], v[68:71]
	global_load_dwordx4 v[240:243], v[8:9], off offset:704
	s_nop 0
	s_waitcnt vmcnt(7)
	v_mfma_f32_16x16x32_bf16 v[80:83], v[84:87], v[244:247], v[80:83]
	global_load_dwordx4 v[244:247], v[6:7], off offset:704
	s_nop 0
	s_waitcnt vmcnt(7)
	v_mfma_f32_16x16x32_bf16 v[24:27], v[84:87], v[248:251], v[24:27]
	global_load_dwordx4 v[248:251], v[4:5], off offset:704
	ds_read_b128 v[84:87], v20 offset:640
	s_waitcnt lgkmcnt(0)
	s_waitcnt vmcnt(7)
	v_mfma_f32_16x16x32_bf16 v[64:67], v[84:87], v[220:223], v[64:67]
	global_load_dwordx4 v[220:223], v[10:11], off offset:768
	s_nop 0
	s_waitcnt vmcnt(7)
	v_mfma_f32_16x16x32_bf16 v[68:71], v[84:87], v[224:227], v[68:71]
	global_load_dwordx4 v[224:227], v[8:9], off offset:768
	s_nop 0
	s_waitcnt vmcnt(7)
	v_mfma_f32_16x16x32_bf16 v[80:83], v[84:87], v[228:231], v[80:83]
	global_load_dwordx4 v[228:231], v[6:7], off offset:768
	s_nop 0
	s_waitcnt vmcnt(7)
	v_mfma_f32_16x16x32_bf16 v[24:27], v[84:87], v[232:235], v[24:27]
	global_load_dwordx4 v[232:235], v[4:5], off offset:768
	ds_read_b128 v[84:87], v20 offset:704
	s_waitcnt lgkmcnt(0)
	s_waitcnt vmcnt(7)
	v_mfma_f32_16x16x32_bf16 v[64:67], v[84:87], v[236:239], v[64:67]
	global_load_dwordx4 v[236:239], v[10:11], off offset:832
	s_nop 0
	s_waitcnt vmcnt(7)
	v_mfma_f32_16x16x32_bf16 v[68:71], v[84:87], v[240:243], v[68:71]
	global_load_dwordx4 v[240:243], v[8:9], off offset:832
	s_nop 0
	s_waitcnt vmcnt(7)
	v_mfma_f32_16x16x32_bf16 v[80:83], v[84:87], v[244:247], v[80:83]
	global_load_dwordx4 v[244:247], v[6:7], off offset:832
	s_nop 0
	s_waitcnt vmcnt(7)
	v_mfma_f32_16x16x32_bf16 v[24:27], v[84:87], v[248:251], v[24:27]
	global_load_dwordx4 v[248:251], v[4:5], off offset:832
	ds_read_b128 v[84:87], v20 offset:768
	s_waitcnt lgkmcnt(0)
	s_waitcnt vmcnt(7)
	v_mfma_f32_16x16x32_bf16 v[64:67], v[84:87], v[220:223], v[64:67]
	s_nop 0
	s_nop 0
	s_waitcnt vmcnt(6)
	v_mfma_f32_16x16x32_bf16 v[68:71], v[84:87], v[224:227], v[68:71]
	s_nop 0
	s_nop 0
	s_waitcnt vmcnt(5)
	v_mfma_f32_16x16x32_bf16 v[80:83], v[84:87], v[228:231], v[80:83]
	s_nop 0
	s_nop 0
	s_waitcnt vmcnt(4)
	v_mfma_f32_16x16x32_bf16 v[24:27], v[84:87], v[232:235], v[24:27]
	s_nop 0
	ds_read_b128 v[84:87], v20 offset:832
	s_nop 0
	s_waitcnt lgkmcnt(0)
	s_waitcnt vmcnt(2)
	v_mfma_f32_16x16x32_bf16 v[8:11], v[84:87], v[240:243], v[68:71]
	s_nop 2
	s_nop 0
	v_or_b32_e32 v20, 0x10000, v18
	s_nop 0
	s_waitcnt vmcnt(3)
	v_mfma_f32_16x16x32_bf16 v[64:67], v[84:87], v[236:239], v[64:67]
	s_nop 0
	s_waitcnt vmcnt(0)
	v_mfma_f32_16x16x32_bf16 v[4:7], v[84:87], v[248:251], v[24:27]
	s_nop 2
	v_add_u32_e32 v24, v19, v20
	s_nop 1
	ds_write_b32 v24, v64
	v_or_b32_e32 v24, 0x10800, v18
	v_add_u32_e32 v25, v19, v24
	ds_write_b32 v25, v65
	v_or_b32_e32 v25, 0x11000, v18
	v_or_b32_e32 v18, 0x11800, v18
	v_add_u32_e32 v26, v19, v25
	v_add_u32_e32 v19, v19, v18
	ds_write_b32 v19, v67
	v_add_u32_e32 v19, v22, v20
	s_waitcnt vmcnt(1)
	v_mfma_f32_16x16x32_bf16 v[68:71], v[84:87], v[244:247], v[80:83]
	ds_write_b32 v19, v8
	v_add_u32_e32 v8, v22, v24
	ds_write_b32 v8, v9
	v_add_u32_e32 v8, v22, v25
	ds_write_b32 v8, v10
	v_add_u32_e32 v8, v22, v18
	ds_write_b32 v8, v11
	v_add_u32_e32 v8, v23, v20
	ds_write_b32 v8, v68
	v_add_u32_e32 v8, v23, v24
	ds_write_b32 v8, v69
	v_add_u32_e32 v8, v23, v25
	ds_write_b32 v8, v70
	v_add_u32_e32 v8, v23, v18
	ds_write_b32 v8, v71
	v_add_u32_e32 v8, v21, v20
	ds_write_b32 v8, v4
	v_add_u32_e32 v4, v21, v24
	ds_write_b32 v4, v5
	v_add_u32_e32 v4, v21, v25
	ds_write_b32 v4, v6
	v_add_u32_e32 v4, v21, v18
	ds_write_b32 v4, v7
	v_lshl_add_u32 v4, v16, 2, 0
	v_add_u32_e32 v5, 0x14000, v4
	ds_write_b32 v26, v66
	s_waitcnt lgkmcnt(0)
	s_barrier
; DEVI float bf2f(bf16_t b) { return __uint_as_float(((unsigned)b) << 16); }
; DEVI void rwkv_prep(const Params& p, int l, unsigned char* smem, int item) {
;     ...
;     float wacc[16], aacc[16], gacc[16];
; #pragma unroll
;     for (int t = 0; t < 16; ++t) { wacc[t] = sAcc[t * 512 + c]; aacc[t] = sAcc[(16 + t) * 512 + c]; gacc[t] = sAcc[(32 + t) * 512 + c]; }
;     __syncthreads();
; #pragma unroll
;     for (int t = 0; t < 16; ++t) { const float x = bf2f(xv[t + 1]), xp = bf2f(xv[t]); sVx[c * 16 + t] = x + (xp - x) * mu_v; }
;     __syncthreads();
;     float vacc[16];
; #pragma unroll
;     for (int t = 0; t < 16; ++t) vacc[t] = 0.f;
;     if (l > 0) {
;         const float* v1 = (const float*)p.in[22];
;         const float* v2 = (const float*)p.in[23];
;         {
;             const int m = tid & 63, cp = tid >> 6;
;             float ma[16];
; #pragma unroll
;             for (int t = 0; t < 16; ++t) ma[t] = 0.f;
; #pragma unroll 8
;             for (int cc = 0; cc < 64; ++cc) {
;                 const float w = v1[(cp * 64 + cc) * 64 + m]; const f32x4* lp = (const f32x4*)(sVx + (cp * 64 + cc) * 16);
; #pragma unroll
;                 for (int q = 0; q < 4; ++q) { const f32x4 x = lp[q]; ma[4 * q] += x[0] * w; ma[4 * q + 1] += x[1] * w; ma[4 * q + 2] += x[2] * w; ma[4 * q + 3] += x[3] * w; }
;             }
;             float* sP = sMid + 64 * 16;
; #pragma unroll
;             for (int q = 0; q < 4; ++q) *(f32x4*)(sP + (cp * 64 + m) * 16 + 4 * q) = (f32x4){ma[4 * q], ma[4 * q + 1], ma[4 * q + 2], ma[4 * q + 3]};
	ds_read2st64_b32 v[72:73], v4 offset0:64 offset1:72
	ds_read2st64_b32 v[70:71], v4 offset0:192 offset1:200
	ds_read_b32 v104, v5
	v_add_u32_e32 v5, 0x14800, v4
	ds_read_b32 v103, v5
	ds_read2st64_b32 v[68:69], v4 offset0:80 offset1:88
	ds_read2st64_b32 v[66:67], v4 offset0:208 offset1:216
	v_add_u32_e32 v5, 0x15000, v4
	ds_read_b32 v102, v5
	v_add_u32_e32 v5, 0x15800, v4
	ds_read_b32 v101, v5
	ds_read2st64_b32 v[64:65], v4 offset0:96 offset1:104
	ds_read2st64_b32 v[44:45], v4 offset0:224 offset1:232
	v_add_u32_e32 v5, 0x16000, v4
	ds_read_b32 v100, v5
	v_add_u32_e32 v5, 0x16800, v4
	ds_read_b32 v99, v5
	ds_read2st64_b32 v[28:29], v4 offset0:112 offset1:120
	ds_read2st64_b32 v[26:27], v4 offset0:240 offset1:248
	v_add_u32_e32 v5, 0x17000, v4
	ds_read_b32 v98, v5
	v_add_u32_e32 v5, 0x17800, v4
	ds_read_b32 v97, v5
	ds_read2st64_b32 v[24:25], v4 offset0:128 offset1:136
	v_add_u32_e32 v5, 0x10000, v4
	ds_read_b32 v96, v5
	v_add_u32_e32 v5, 0x18000, v4
	ds_read_b32 v95, v5
	v_add_u32_e32 v5, 0x10800, v4
	ds_read_b32 v94, v5
	v_add_u32_e32 v5, 0x18800, v4
	ds_read_b32 v93, v5
	ds_read2st64_b32 v[22:23], v4 offset0:144 offset1:152
	v_add_u32_e32 v5, 0x11000, v4
	ds_read_b32 v92, v5
	v_add_u32_e32 v5, 0x19000, v4
	ds_read_b32 v91, v5
	v_add_u32_e32 v5, 0x11800, v4
	ds_read_b32 v90, v5
	v_add_u32_e32 v5, 0x19800, v4
	ds_read_b32 v89, v5
	ds_read2st64_b32 v[20:21], v4 offset0:160 offset1:168
	v_add_u32_e32 v5, 0x12000, v4
	ds_read_b32 v88, v5
	v_add_u32_e32 v5, 0x1a000, v4
	ds_read_b32 v87, v5
	v_add_u32_e32 v5, 0x12800, v4
	ds_read_b32 v86, v5
	v_add_u32_e32 v5, 0x1a800, v4
	ds_read_b32 v85, v5
	ds_read2st64_b32 v[18:19], v4 offset0:176 offset1:184
	v_add_u32_e32 v5, 0x13000, v4
	ds_read_b32 v84, v5
	v_add_u32_e32 v5, 0x1b000, v4
	ds_read_b32 v82, v5
	v_add_u32_e32 v5, 0x13800, v4
	v_add_u32_e32 v4, 0x1b800, v4
	ds_read_b32 v81, v5
	ds_read_b32 v80, v4
	v_lshlrev_b32_e32 v4, 16, v3
	v_lshlrev_b32_e32 v5, 16, v110
	v_mov_b32_e32 v3, v4
	v_pk_add_f32 v[2:3], v[2:3], v[4:5] neg_lo:[0,1] neg_hi:[0,1]
	v_lshlrev_b32_e32 v7, 16, v109
	v_lshlrev_b32_e32 v6, 16, v108
	v_pk_fma_f32 v[2:3], v[0:1], v[2:3], v[4:5] op_sel_hi:[0,1,1]
	v_pk_mov_b32 v[4:5], v[4:5], v[6:7] op_sel:[1,0]
	v_lshlrev_b32_e32 v8, 6, v16
	v_pk_add_f32 v[4:5], v[4:5], v[6:7] neg_lo:[0,1] neg_hi:[0,1]
	v_add_u32_e32 v83, 0, v8
	v_pk_fma_f32 v[4:5], v[0:1], v[4:5], v[6:7] op_sel_hi:[0,1,1]
	s_waitcnt lgkmcnt(0)
	s_barrier
	ds_write_b128 v83, v[2:5] offset:16384
	v_lshlrev_b32_e32 v5, 16, v107
	v_lshlrev_b32_e32 v4, 16, v106
	v_pk_mov_b32 v[2:3], v[6:7], v[4:5] op_sel:[1,0]
	v_lshlrev_b32_e32 v7, 16, v105
	v_pk_add_f32 v[2:3], v[2:3], v[4:5] neg_lo:[0,1] neg_hi:[0,1]
	v_lshlrev_b32_e32 v6, 16, v77
	v_pk_fma_f32 v[2:3], v[0:1], v[2:3], v[4:5] op_sel_hi:[0,1,1]
	v_pk_mov_b32 v[4:5], v[4:5], v[6:7] op_sel:[1,0]
	s_nop 0
	v_pk_add_f32 v[4:5], v[4:5], v[6:7] neg_lo:[0,1] neg_hi:[0,1]
	s_nop 0
	v_pk_fma_f32 v[4:5], v[0:1], v[4:5], v[6:7] op_sel_hi:[0,1,1]
	ds_write_b128 v83, v[2:5] offset:16400
	v_lshlrev_b32_e32 v5, 16, v76
	v_lshlrev_b32_e32 v4, 16, v75
	v_pk_mov_b32 v[2:3], v[6:7], v[4:5] op_sel:[1,0]
	v_lshlrev_b32_e32 v7, 16, v74
	v_pk_add_f32 v[2:3], v[2:3], v[4:5] neg_lo:[0,1] neg_hi:[0,1]
	v_lshlrev_b32_e32 v6, 16, v15
	v_pk_fma_f32 v[2:3], v[0:1], v[2:3], v[4:5] op_sel_hi:[0,1,1]
	v_pk_mov_b32 v[4:5], v[4:5], v[6:7] op_sel:[1,0]
	s_nop 0
	v_pk_add_f32 v[4:5], v[4:5], v[6:7] neg_lo:[0,1] neg_hi:[0,1]
	s_nop 0
	v_pk_fma_f32 v[4:5], v[0:1], v[4:5], v[6:7] op_sel_hi:[0,1,1]
	ds_write_b128 v83, v[2:5] offset:16416
	v_lshlrev_b32_e32 v5, 16, v14
	v_lshlrev_b32_e32 v4, 16, v13
	v_pk_mov_b32 v[2:3], v[6:7], v[4:5] op_sel:[1,0]
	v_lshlrev_b32_e32 v6, 16, v12
	v_pk_add_f32 v[2:3], v[2:3], v[4:5] neg_lo:[0,1] neg_hi:[0,1]
	v_lshlrev_b32_e32 v7, 16, v1
	v_pk_fma_f32 v[2:3], v[0:1], v[2:3], v[4:5] op_sel_hi:[0,1,1]
	v_pk_mov_b32 v[4:5], v[4:5], v[6:7] op_sel:[1,0]
	s_nop 0
	v_pk_add_f32 v[4:5], v[4:5], v[6:7] neg_lo:[0,1] neg_hi:[0,1]
	s_nop 0
	v_pk_fma_f32 v[4:5], v[0:1], v[4:5], v[6:7] op_sel_hi:[0,1,1]
	v_mov_b32_e32 v1, 0
	v_cndmask_b32_e64 v0, 0, 1, s[0:1]
	ds_write_b128 v83, v[2:5] offset:16432
	v_cmp_ne_u32_e64 s[6:7], 1, v0
	v_mov_b32_e32 v0, v1
	v_mov_b32_e32 v3, v1
	v_mov_b32_e32 v2, v1
	v_mov_b32_e32 v5, v1
	v_mov_b32_e32 v4, v1
	v_mov_b32_e32 v7, v1
	v_mov_b32_e32 v6, v1
	v_mov_b32_e32 v11, v1
	v_mov_b32_e32 v10, v1
	v_mov_b32_e32 v13, v1
	v_mov_b32_e32 v12, v1
	v_mov_b32_e32 v15, v1
	v_mov_b32_e32 v14, v1
	v_mov_b32_e32 v75, v1
	v_mov_b32_e32 v74, v1
	s_waitcnt lgkmcnt(0)
	s_barrier
	s_cbranch_vccnz .LBB0_413
	v_and_b32_e32 v0, 63, v16
	v_and_b32_e32 v1, 0xfffff000, v8
	v_ashrrev_i32_e32 v75, 31, v1
	v_or_b32_e32 v74, v1, v0
	s_add_i32 s0, 0, 0x4000
	v_mov_b32_e32 v10, 0
	v_mov_b32_e32 v105, v16
	v_lshl_add_u64 v[76:77], v[74:75], 2, s[64:65]
	v_add_u32_e32 v106, s0, v1
	s_mov_b64 s[8:9], 0
	v_mov_b32_e32 v11, v10
	v_mov_b32_e32 v0, v10
	v_mov_b32_e32 v1, v10
	v_mov_b32_e32 v2, v10
	v_mov_b32_e32 v3, v10
	v_mov_b32_e32 v4, v10
	v_mov_b32_e32 v5, v10
	v_mov_b32_e32 v6, v10
	v_mov_b32_e32 v7, v10
	v_mov_b32_e32 v12, v10
	v_mov_b32_e32 v13, v10
	v_mov_b32_e32 v14, v10
	v_mov_b32_e32 v15, v10
	v_mov_b32_e32 v8, v10
	v_mov_b32_e32 v9, v10
; DEVI void rwkv_prep(const Params& p, int l, unsigned char* smem, int item) {
;     ...
; #pragma unroll 8
;             for (int cc = 0; cc < 64; ++cc) {
;                 const float w = v1[(cp * 64 + cc) * 64 + m]; const f32x4* lp = (const f32x4*)(sVx + (cp * 64 + cc) * 16);
; #pragma unroll
;                 for (int q = 0; q < 4; ++q) { const f32x4 x = lp[q]; ma[4 * q] += x[0] * w; ma[4 * q + 1] += x[1] * w; ma[4 * q + 2] += x[2] * w; ma[4 * q + 3] += x[3] * w; }
;             }
.LBB0_400:
	v_lshl_add_u64 v[244:245], v[76:77], 0, s[8:9]
	global_load_dword v220, v[244:245], off
	global_load_dword v221, v[244:245], off offset:256
	global_load_dword v222, v[244:245], off offset:512
	global_load_dword v223, v[244:245], off offset:768
	global_load_dword v224, v[244:245], off offset:1024
	global_load_dword v225, v[244:245], off offset:1280
	global_load_dword v226, v[244:245], off offset:1536
	global_load_dword v227, v[244:245], off offset:1792
	ds_read_b128 v[108:111], v106
	ds_read_b128 v[112:115], v106 offset:16
	ds_read_b128 v[116:119], v106 offset:32
	ds_read_b128 v[120:123], v106 offset:48
	ds_read_b128 v[228:231], v106 offset:64
	ds_read_b128 v[232:235], v106 offset:80
	ds_read_b128 v[236:239], v106 offset:96
	ds_read_b128 v[240:243], v106 offset:112
	v_add_u32_e32 v74, 0x200, v74
	s_add_u32 s8, s8, 0x800
	s_addc_u32 s9, s9, 0
	s_waitcnt vmcnt(7) lgkmcnt(4)
	v_pk_fma_f32 v[0:1], v[220:221], v[108:109], v[0:1] op_sel_hi:[0,1,1]
	v_pk_fma_f32 v[2:3], v[220:221], v[110:111], v[2:3] op_sel_hi:[0,1,1]
	v_pk_fma_f32 v[4:5], v[220:221], v[112:113], v[4:5] op_sel_hi:[0,1,1]
	v_pk_fma_f32 v[6:7], v[220:221], v[114:115], v[6:7] op_sel_hi:[0,1,1]
	v_pk_fma_f32 v[12:13], v[220:221], v[116:117], v[12:13] op_sel_hi:[0,1,1]
	v_pk_fma_f32 v[14:15], v[220:221], v[118:119], v[14:15] op_sel_hi:[0,1,1]
	v_pk_fma_f32 v[8:9], v[220:221], v[120:121], v[8:9] op_sel_hi:[0,1,1]
	v_pk_fma_f32 v[10:11], v[220:221], v[122:123], v[10:11] op_sel_hi:[0,1,1]
	ds_read_b128 v[108:111], v106 offset:128
	ds_read_b128 v[112:115], v106 offset:144
	ds_read_b128 v[116:119], v106 offset:160
	ds_read_b128 v[120:123], v106 offset:176
	s_waitcnt vmcnt(6) lgkmcnt(4)
	v_pk_fma_f32 v[0:1], v[220:221], v[228:229], v[0:1] op_sel:[1,0,0] op_sel_hi:[1,1,1]
	v_pk_fma_f32 v[2:3], v[220:221], v[230:231], v[2:3] op_sel:[1,0,0] op_sel_hi:[1,1,1]
	v_pk_fma_f32 v[4:5], v[220:221], v[232:233], v[4:5] op_sel:[1,0,0] op_sel_hi:[1,1,1]
	v_pk_fma_f32 v[6:7], v[220:221], v[234:235], v[6:7] op_sel:[1,0,0] op_sel_hi:[1,1,1]
	v_pk_fma_f32 v[12:13], v[220:221], v[236:237], v[12:13] op_sel:[1,0,0] op_sel_hi:[1,1,1]
	v_pk_fma_f32 v[14:15], v[220:221], v[238:239], v[14:15] op_sel:[1,0,0] op_sel_hi:[1,1,1]
	v_pk_fma_f32 v[8:9], v[220:221], v[240:241], v[8:9] op_sel:[1,0,0] op_sel_hi:[1,1,1]
	v_pk_fma_f32 v[10:11], v[220:221], v[242:243], v[10:11] op_sel:[1,0,0] op_sel_hi:[1,1,1]
	ds_read_b128 v[228:231], v106 offset:192
	ds_read_b128 v[232:235], v106 offset:208
	ds_read_b128 v[236:239], v106 offset:224
	ds_read_b128 v[240:243], v106 offset:240
	s_waitcnt vmcnt(5) lgkmcnt(4)
	v_pk_fma_f32 v[0:1], v[222:223], v[108:109], v[0:1] op_sel_hi:[0,1,1]
	v_pk_fma_f32 v[2:3], v[222:223], v[110:111], v[2:3] op_sel_hi:[0,1,1]
	v_pk_fma_f32 v[4:5], v[222:223], v[112:113], v[4:5] op_sel_hi:[0,1,1]
	v_pk_fma_f32 v[6:7], v[222:223], v[114:115], v[6:7] op_sel_hi:[0,1,1]
	v_pk_fma_f32 v[12:13], v[222:223], v[116:117], v[12:13] op_sel_hi:[0,1,1]
	v_pk_fma_f32 v[14:15], v[222:223], v[118:119], v[14:15] op_sel_hi:[0,1,1]
	v_pk_fma_f32 v[8:9], v[222:223], v[120:121], v[8:9] op_sel_hi:[0,1,1]
	v_pk_fma_f32 v[10:11], v[222:223], v[122:123], v[10:11] op_sel_hi:[0,1,1]
	ds_read_b128 v[108:111], v106 offset:256
	ds_read_b128 v[112:115], v106 offset:272
	ds_read_b128 v[116:119], v106 offset:288
	ds_read_b128 v[120:123], v106 offset:304
	s_waitcnt vmcnt(4) lgkmcnt(4)
	v_pk_fma_f32 v[0:1], v[222:223], v[228:229], v[0:1] op_sel:[1,0,0] op_sel_hi:[1,1,1]
	v_pk_fma_f32 v[2:3], v[222:223], v[230:231], v[2:3] op_sel:[1,0,0] op_sel_hi:[1,1,1]
	v_pk_fma_f32 v[4:5], v[222:223], v[232:233], v[4:5] op_sel:[1,0,0] op_sel_hi:[1,1,1]
	v_pk_fma_f32 v[6:7], v[222:223], v[234:235], v[6:7] op_sel:[1,0,0] op_sel_hi:[1,1,1]
	v_pk_fma_f32 v[12:13], v[222:223], v[236:237], v[12:13] op_sel:[1,0,0] op_sel_hi:[1,1,1]
	v_pk_fma_f32 v[14:15], v[222:223], v[238:239], v[14:15] op_sel:[1,0,0] op_sel_hi:[1,1,1]
	v_pk_fma_f32 v[8:9], v[222:223], v[240:241], v[8:9] op_sel:[1,0,0] op_sel_hi:[1,1,1]
	v_pk_fma_f32 v[10:11], v[222:223], v[242:243], v[10:11] op_sel:[1,0,0] op_sel_hi:[1,1,1]
	ds_read_b128 v[228:231], v106 offset:320
	ds_read_b128 v[232:235], v106 offset:336
	ds_read_b128 v[236:239], v106 offset:352
	ds_read_b128 v[240:243], v106 offset:368
	s_waitcnt vmcnt(3) lgkmcnt(4)
	v_pk_fma_f32 v[0:1], v[224:225], v[108:109], v[0:1] op_sel_hi:[0,1,1]
	v_pk_fma_f32 v[2:3], v[224:225], v[110:111], v[2:3] op_sel_hi:[0,1,1]
	v_pk_fma_f32 v[4:5], v[224:225], v[112:113], v[4:5] op_sel_hi:[0,1,1]
	v_pk_fma_f32 v[6:7], v[224:225], v[114:115], v[6:7] op_sel_hi:[0,1,1]
	v_pk_fma_f32 v[12:13], v[224:225], v[116:117], v[12:13] op_sel_hi:[0,1,1]
	v_pk_fma_f32 v[14:15], v[224:225], v[118:119], v[14:15] op_sel_hi:[0,1,1]
	v_pk_fma_f32 v[8:9], v[224:225], v[120:121], v[8:9] op_sel_hi:[0,1,1]
	v_pk_fma_f32 v[10:11], v[224:225], v[122:123], v[10:11] op_sel_hi:[0,1,1]
	ds_read_b128 v[108:111], v106 offset:384
	ds_read_b128 v[112:115], v106 offset:400
	ds_read_b128 v[116:119], v106 offset:416
	ds_read_b128 v[120:123], v106 offset:432
	s_waitcnt vmcnt(2) lgkmcnt(4)
; DEVI void rwkv_prep(const Params& p, int l, unsigned char* smem, int item) {
;     ...
; #pragma unroll 8
;             for (int cc = 0; cc < 64; ++cc) {
;                 const float w = v1[(cp * 64 + cc) * 64 + m]; const f32x4* lp = (const f32x4*)(sVx + (cp * 64 + cc) * 16);
; #pragma unroll
;                 for (int q = 0; q < 4; ++q) { const f32x4 x = lp[q]; ma[4 * q] += x[0] * w; ma[4 * q + 1] += x[1] * w; ma[4 * q + 2] += x[2] * w; ma[4 * q + 3] += x[3] * w; }
;             }
;             float* sP = sMid + 64 * 16;
; #pragma unroll
;             for (int q = 0; q < 4; ++q) *(f32x4*)(sP + (cp * 64 + m) * 16 + 4 * q) = (f32x4){ma[4 * q], ma[4 * q + 1], ma[4 * q + 2], ma[4 * q + 3]};
;             __syncthreads();
;             for (int e = tid; e < 1024; e += NT) {
;                 float a = 0.f;
; #pragma unroll
;                 for (int k = 0; k < 8; ++k) a += sP[k * 1024 + e];
;                 sMid[e] = a;
;             }
	v_pk_fma_f32 v[0:1], v[224:225], v[228:229], v[0:1] op_sel:[1,0,0] op_sel_hi:[1,1,1]
	v_pk_fma_f32 v[2:3], v[224:225], v[230:231], v[2:3] op_sel:[1,0,0] op_sel_hi:[1,1,1]
	v_pk_fma_f32 v[4:5], v[224:225], v[232:233], v[4:5] op_sel:[1,0,0] op_sel_hi:[1,1,1]
	v_pk_fma_f32 v[6:7], v[224:225], v[234:235], v[6:7] op_sel:[1,0,0] op_sel_hi:[1,1,1]
	v_pk_fma_f32 v[12:13], v[224:225], v[236:237], v[12:13] op_sel:[1,0,0] op_sel_hi:[1,1,1]
	v_pk_fma_f32 v[14:15], v[224:225], v[238:239], v[14:15] op_sel:[1,0,0] op_sel_hi:[1,1,1]
	v_pk_fma_f32 v[8:9], v[224:225], v[240:241], v[8:9] op_sel:[1,0,0] op_sel_hi:[1,1,1]
	v_pk_fma_f32 v[10:11], v[224:225], v[242:243], v[10:11] op_sel:[1,0,0] op_sel_hi:[1,1,1]
	ds_read_b128 v[228:231], v106 offset:448
	ds_read_b128 v[232:235], v106 offset:464
	ds_read_b128 v[236:239], v106 offset:480
	ds_read_b128 v[240:243], v106 offset:496
	s_waitcnt vmcnt(1) lgkmcnt(4)
	v_pk_fma_f32 v[0:1], v[226:227], v[108:109], v[0:1] op_sel_hi:[0,1,1]
	v_pk_fma_f32 v[2:3], v[226:227], v[110:111], v[2:3] op_sel_hi:[0,1,1]
	v_pk_fma_f32 v[4:5], v[226:227], v[112:113], v[4:5] op_sel_hi:[0,1,1]
	v_pk_fma_f32 v[6:7], v[226:227], v[114:115], v[6:7] op_sel_hi:[0,1,1]
	v_pk_fma_f32 v[12:13], v[226:227], v[116:117], v[12:13] op_sel_hi:[0,1,1]
	v_pk_fma_f32 v[14:15], v[226:227], v[118:119], v[14:15] op_sel_hi:[0,1,1]
	v_pk_fma_f32 v[8:9], v[226:227], v[120:121], v[8:9] op_sel_hi:[0,1,1]
	v_pk_fma_f32 v[10:11], v[226:227], v[122:123], v[10:11] op_sel_hi:[0,1,1]
	s_waitcnt vmcnt(0) lgkmcnt(0)
	v_pk_fma_f32 v[0:1], v[226:227], v[228:229], v[0:1] op_sel:[1,0,0] op_sel_hi:[1,1,1]
	v_pk_fma_f32 v[2:3], v[226:227], v[230:231], v[2:3] op_sel:[1,0,0] op_sel_hi:[1,1,1]
	v_pk_fma_f32 v[4:5], v[226:227], v[232:233], v[4:5] op_sel:[1,0,0] op_sel_hi:[1,1,1]
	v_pk_fma_f32 v[6:7], v[226:227], v[234:235], v[6:7] op_sel:[1,0,0] op_sel_hi:[1,1,1]
	v_pk_fma_f32 v[12:13], v[226:227], v[236:237], v[12:13] op_sel:[1,0,0] op_sel_hi:[1,1,1]
	v_pk_fma_f32 v[14:15], v[226:227], v[238:239], v[14:15] op_sel:[1,0,0] op_sel_hi:[1,1,1]
	v_pk_fma_f32 v[8:9], v[226:227], v[240:241], v[8:9] op_sel:[1,0,0] op_sel_hi:[1,1,1]
	v_pk_fma_f32 v[10:11], v[226:227], v[242:243], v[10:11] op_sel:[1,0,0] op_sel_hi:[1,1,1]
	s_cmpk_eq_i32 s8, 0x4000
	v_add_u32_e32 v106, 0x200, v106
	s_cbranch_scc0 .LBB0_400
	s_movk_i32 s0, 0x400
	v_cmp_gt_i32_e32 vcc, s0, v16
	ds_write_b128 v83, v[0:3] offset:53248
	ds_write_b128 v83, v[4:7] offset:53264
	ds_write_b128 v83, v[12:15] offset:53280
	ds_write_b128 v83, v[8:11] offset:53296
	s_waitcnt lgkmcnt(0)
	s_barrier
	s_and_saveexec_b64 s[68:69], vcc
	s_cbranch_execz .LBB0_411
	v_max_i32_e32 v0, 0x200, v16
	v_sub_u32_e32 v0, v0, v16
	v_add_u32_e32 v2, 0x1ff, v0
	s_mov_b32 s0, 0x9600
	v_cmp_gt_u32_e64 s[70:71], s0, v2
	s_mov_b32 s0, 0x95ff
	v_cmp_lt_u32_e32 vcc, s0, v2
	s_and_saveexec_b64 s[0:1], vcc
	s_cbranch_execz .LBB0_408
	v_lshrrev_b32_e32 v1, 9, v2
	v_lshlrev_b32_e32 v3, 2, v16
	v_add_u32_e32 v0, 0, v3
	v_lshlrev_b32_e32 v5, 11, v1
	v_add_u32_e32 v6, v0, v5
	v_add_u32_e32 v4, 0xd000, v0
	v_add_u32_e32 v7, 0xd000, v6
	v_cmp_ge_u32_e32 vcc, v7, v4
	v_add_u32_e32 v4, 0xe000, v0
	v_cmp_gt_u32_e64 s[8:9], 2.0, v2
	v_add_u32_e32 v2, 0xe000, v6
	v_cmp_ge_u32_e64 s[10:11], v2, v4
	s_and_b64 s[2:3], s[10:11], vcc
	v_add_u32_e32 v2, 0xf000, v0
	v_add_u32_e32 v4, 0xf000, v6
	s_add_i32 s10, 0, 0x10000
	v_cmp_ge_u32_e32 vcc, v4, v2
	v_add_u32_e32 v2, s10, v3
	v_add_u32_e32 v4, v2, v5
	s_add_i32 s12, 0, 0x11000
	v_cmp_ge_u32_e64 s[10:11], v4, v2
	v_add_u32_e32 v2, s12, v3
	v_add_u32_e32 v4, v2, v5
	s_add_i32 s14, 0, 0x12000
	v_cmp_ge_u32_e64 s[12:13], v4, v2
	v_add_u32_e32 v2, s14, v3
	v_add_u32_e32 v4, v2, v5
	s_add_i32 s16, 0, 0x13000
	s_and_b64 s[2:3], s[2:3], s[8:9]
	v_cmp_ge_u32_e64 s[14:15], v4, v2
	v_add_u32_e32 v2, s16, v3
	s_and_b64 s[2:3], vcc, s[2:3]
	v_add_u32_e32 v4, v2, v5
	s_add_i32 s18, 0, 0x14000
	s_and_b64 s[2:3], s[10:11], s[2:3]
	v_cmp_ge_u32_e64 s[16:17], v4, v2
	v_add_u32_e32 v2, s18, v3
	s_and_b64 s[2:3], s[12:13], s[2:3]
	v_add_u32_e32 v3, v2, v5
	s_and_b64 s[2:3], s[14:15], s[2:3]
	v_cmp_ge_u32_e64 s[18:19], v3, v2
	s_and_b64 s[2:3], s[16:17], s[2:3]
	s_and_b64 s[2:3], s[18:19], s[2:3]
	s_mov_b64 s[10:11], -1
	s_and_saveexec_b64 s[8:9], s[2:3]
	s_cbranch_execz .LBB0_407
	v_add_u32_e32 v1, 1, v1
	v_and_b32_e32 v2, 0xfffffe, v1
	s_mov_b64 s[10:11], 0
	v_mov_b32_e32 v3, v2

; DEVI void rwkv_prep(const Params& p, int l, unsigned char* smem, int item) {
;     ...
; #pragma unroll 8
;         for (int m = 0; m < 64; ++m) {
;             const float w = v2[m * 512 + c]; const f32x4* lp = (const f32x4*)(sMid + m * 16);
; #pragma unroll
;             for (int q = 0; q < 4; ++q) { const f32x4 x = lp[q]; vacc[4 * q] += x[0] * w; vacc[4 * q + 1] += x[1] * w; vacc[4 * q + 2] += x[2] * w; vacc[4 * q + 3] += x[3] * w; }
;         }
.LBB0_412:
	v_add_u32_e32 v76, s1, v16
	v_mov_b32_e32 v105, s0
	v_mov_b32_e32 v244, v76
	v_ashrrev_i32_e32 v245, 31, v244
	v_lshl_add_u64 v[244:245], v[244:245], 2, s[66:67]
	global_load_dword v220, v[244:245], off
	v_add_u32_e32 v244, 0x200, v76
	v_ashrrev_i32_e32 v245, 31, v244
	v_lshl_add_u64 v[244:245], v[244:245], 2, s[66:67]
	global_load_dword v221, v[244:245], off
	v_add_u32_e32 v244, 0x400, v76
	v_ashrrev_i32_e32 v245, 31, v244
	v_lshl_add_u64 v[244:245], v[244:245], 2, s[66:67]
	global_load_dword v222, v[244:245], off
	v_add_u32_e32 v244, 0x600, v76
	v_ashrrev_i32_e32 v245, 31, v244
	v_lshl_add_u64 v[244:245], v[244:245], 2, s[66:67]
	global_load_dword v223, v[244:245], off
	v_add_u32_e32 v244, 0x800, v76
	v_ashrrev_i32_e32 v245, 31, v244
	v_lshl_add_u64 v[244:245], v[244:245], 2, s[66:67]
	global_load_dword v224, v[244:245], off
	v_add_u32_e32 v244, 0xa00, v76
	v_ashrrev_i32_e32 v245, 31, v244
	v_lshl_add_u64 v[244:245], v[244:245], 2, s[66:67]
	global_load_dword v225, v[244:245], off
	v_add_u32_e32 v244, 0xc00, v76
	v_ashrrev_i32_e32 v245, 31, v244
	v_lshl_add_u64 v[244:245], v[244:245], 2, s[66:67]
	global_load_dword v226, v[244:245], off
	v_add_u32_e32 v244, 0xe00, v76
	v_ashrrev_i32_e32 v245, 31, v244
	v_lshl_add_u64 v[244:245], v[244:245], 2, s[66:67]
	global_load_dword v227, v[244:245], off
	ds_read_b128 v[106:109], v105
	ds_read_b128 v[110:113], v105 offset:16
	ds_read_b128 v[114:117], v105 offset:32
	ds_read_b128 v[118:121], v105 offset:48
	ds_read_b128 v[228:231], v105 offset:64
	ds_read_b128 v[232:235], v105 offset:80
	ds_read_b128 v[236:239], v105 offset:96
	ds_read_b128 v[240:243], v105 offset:112
	s_waitcnt vmcnt(7) lgkmcnt(4)
	v_pk_fma_f32 v[74:75], v[220:221], v[106:107], v[74:75] op_sel_hi:[0,1,1]
	v_pk_fma_f32 v[14:15], v[220:221], v[108:109], v[14:15] op_sel_hi:[0,1,1]
	v_pk_fma_f32 v[12:13], v[220:221], v[110:111], v[12:13] op_sel_hi:[0,1,1]
	v_pk_fma_f32 v[10:11], v[220:221], v[112:113], v[10:11] op_sel_hi:[0,1,1]
	v_pk_fma_f32 v[6:7], v[220:221], v[114:115], v[6:7] op_sel_hi:[0,1,1]
	v_pk_fma_f32 v[4:5], v[220:221], v[116:117], v[4:5] op_sel_hi:[0,1,1]
	v_pk_fma_f32 v[2:3], v[220:221], v[118:119], v[2:3] op_sel_hi:[0,1,1]
	v_pk_fma_f32 v[0:1], v[220:221], v[120:121], v[0:1] op_sel_hi:[0,1,1]
	ds_read_b128 v[106:109], v105 offset:128
	ds_read_b128 v[110:113], v105 offset:144
	ds_read_b128 v[114:117], v105 offset:160
	ds_read_b128 v[118:121], v105 offset:176
	s_waitcnt vmcnt(6) lgkmcnt(4)
	v_pk_fma_f32 v[74:75], v[220:221], v[228:229], v[74:75] op_sel:[1,0,0] op_sel_hi:[1,1,1]
	v_pk_fma_f32 v[14:15], v[220:221], v[230:231], v[14:15] op_sel:[1,0,0] op_sel_hi:[1,1,1]
	v_pk_fma_f32 v[12:13], v[220:221], v[232:233], v[12:13] op_sel:[1,0,0] op_sel_hi:[1,1,1]
	v_pk_fma_f32 v[10:11], v[220:221], v[234:235], v[10:11] op_sel:[1,0,0] op_sel_hi:[1,1,1]
	v_pk_fma_f32 v[6:7], v[220:221], v[236:237], v[6:7] op_sel:[1,0,0] op_sel_hi:[1,1,1]
	v_pk_fma_f32 v[4:5], v[220:221], v[238:239], v[4:5] op_sel:[1,0,0] op_sel_hi:[1,1,1]
	v_pk_fma_f32 v[2:3], v[220:221], v[240:241], v[2:3] op_sel:[1,0,0] op_sel_hi:[1,1,1]
	v_pk_fma_f32 v[0:1], v[220:221], v[242:243], v[0:1] op_sel:[1,0,0] op_sel_hi:[1,1,1]
	ds_read_b128 v[228:231], v105 offset:192
	ds_read_b128 v[232:235], v105 offset:208
	ds_read_b128 v[236:239], v105 offset:224
	ds_read_b128 v[240:243], v105 offset:240
	s_waitcnt vmcnt(5) lgkmcnt(4)
	v_pk_fma_f32 v[74:75], v[222:223], v[106:107], v[74:75] op_sel_hi:[0,1,1]
	v_pk_fma_f32 v[14:15], v[222:223], v[108:109], v[14:15] op_sel_hi:[0,1,1]
	v_pk_fma_f32 v[12:13], v[222:223], v[110:111], v[12:13] op_sel_hi:[0,1,1]
	v_pk_fma_f32 v[10:11], v[222:223], v[112:113], v[10:11] op_sel_hi:[0,1,1]
	v_pk_fma_f32 v[6:7], v[222:223], v[114:115], v[6:7] op_sel_hi:[0,1,1]
	v_pk_fma_f32 v[4:5], v[222:223], v[116:117], v[4:5] op_sel_hi:[0,1,1]
	v_pk_fma_f32 v[2:3], v[222:223], v[118:119], v[2:3] op_sel_hi:[0,1,1]
	v_pk_fma_f32 v[0:1], v[222:223], v[120:121], v[0:1] op_sel_hi:[0,1,1]
	ds_read_b128 v[106:109], v105 offset:256
	ds_read_b128 v[110:113], v105 offset:272
	ds_read_b128 v[114:117], v105 offset:288
	ds_read_b128 v[118:121], v105 offset:304
	s_waitcnt vmcnt(4) lgkmcnt(4)
; DEVI void rwkv_prep(const Params& p, int l, unsigned char* smem, int item) {
;     ...
; #pragma unroll 8
;         for (int m = 0; m < 64; ++m) {
;             const float w = v2[m * 512 + c]; const f32x4* lp = (const f32x4*)(sMid + m * 16);
; #pragma unroll
;             for (int q = 0; q < 4; ++q) { const f32x4 x = lp[q]; vacc[4 * q] += x[0] * w; vacc[4 * q + 1] += x[1] * w; vacc[4 * q + 2] += x[2] * w; vacc[4 * q + 3] += x[3] * w; }
;         }
	v_pk_fma_f32 v[74:75], v[222:223], v[228:229], v[74:75] op_sel:[1,0,0] op_sel_hi:[1,1,1]
	v_pk_fma_f32 v[14:15], v[222:223], v[230:231], v[14:15] op_sel:[1,0,0] op_sel_hi:[1,1,1]
	v_pk_fma_f32 v[12:13], v[222:223], v[232:233], v[12:13] op_sel:[1,0,0] op_sel_hi:[1,1,1]
	v_pk_fma_f32 v[10:11], v[222:223], v[234:235], v[10:11] op_sel:[1,0,0] op_sel_hi:[1,1,1]
	v_pk_fma_f32 v[6:7], v[222:223], v[236:237], v[6:7] op_sel:[1,0,0] op_sel_hi:[1,1,1]
	v_pk_fma_f32 v[4:5], v[222:223], v[238:239], v[4:5] op_sel:[1,0,0] op_sel_hi:[1,1,1]
	v_pk_fma_f32 v[2:3], v[222:223], v[240:241], v[2:3] op_sel:[1,0,0] op_sel_hi:[1,1,1]
	v_pk_fma_f32 v[0:1], v[222:223], v[242:243], v[0:1] op_sel:[1,0,0] op_sel_hi:[1,1,1]
	ds_read_b128 v[228:231], v105 offset:320
	ds_read_b128 v[232:235], v105 offset:336
	ds_read_b128 v[236:239], v105 offset:352
	ds_read_b128 v[240:243], v105 offset:368
	s_waitcnt vmcnt(3) lgkmcnt(4)
	v_pk_fma_f32 v[74:75], v[224:225], v[106:107], v[74:75] op_sel_hi:[0,1,1]
	v_pk_fma_f32 v[14:15], v[224:225], v[108:109], v[14:15] op_sel_hi:[0,1,1]
	v_pk_fma_f32 v[12:13], v[224:225], v[110:111], v[12:13] op_sel_hi:[0,1,1]
	v_pk_fma_f32 v[10:11], v[224:225], v[112:113], v[10:11] op_sel_hi:[0,1,1]
	v_pk_fma_f32 v[6:7], v[224:225], v[114:115], v[6:7] op_sel_hi:[0,1,1]
	v_pk_fma_f32 v[4:5], v[224:225], v[116:117], v[4:5] op_sel_hi:[0,1,1]
	v_pk_fma_f32 v[2:3], v[224:225], v[118:119], v[2:3] op_sel_hi:[0,1,1]
	v_pk_fma_f32 v[0:1], v[224:225], v[120:121], v[0:1] op_sel_hi:[0,1,1]
	ds_read_b128 v[106:109], v105 offset:384
	ds_read_b128 v[110:113], v105 offset:400
	ds_read_b128 v[114:117], v105 offset:416
	ds_read_b128 v[118:121], v105 offset:432
	s_waitcnt vmcnt(2) lgkmcnt(4)
	v_pk_fma_f32 v[74:75], v[224:225], v[228:229], v[74:75] op_sel:[1,0,0] op_sel_hi:[1,1,1]
	v_pk_fma_f32 v[14:15], v[224:225], v[230:231], v[14:15] op_sel:[1,0,0] op_sel_hi:[1,1,1]
	v_pk_fma_f32 v[12:13], v[224:225], v[232:233], v[12:13] op_sel:[1,0,0] op_sel_hi:[1,1,1]
	v_pk_fma_f32 v[10:11], v[224:225], v[234:235], v[10:11] op_sel:[1,0,0] op_sel_hi:[1,1,1]
	v_pk_fma_f32 v[6:7], v[224:225], v[236:237], v[6:7] op_sel:[1,0,0] op_sel_hi:[1,1,1]
	v_pk_fma_f32 v[4:5], v[224:225], v[238:239], v[4:5] op_sel:[1,0,0] op_sel_hi:[1,1,1]
	v_pk_fma_f32 v[2:3], v[224:225], v[240:241], v[2:3] op_sel:[1,0,0] op_sel_hi:[1,1,1]
	v_pk_fma_f32 v[0:1], v[224:225], v[242:243], v[0:1] op_sel:[1,0,0] op_sel_hi:[1,1,1]
	ds_read_b128 v[228:231], v105 offset:448
	ds_read_b128 v[232:235], v105 offset:464
	ds_read_b128 v[236:239], v105 offset:480
	ds_read_b128 v[240:243], v105 offset:496
	s_waitcnt vmcnt(1) lgkmcnt(4)
	v_pk_fma_f32 v[74:75], v[226:227], v[106:107], v[74:75] op_sel_hi:[0,1,1]
	v_pk_fma_f32 v[14:15], v[226:227], v[108:109], v[14:15] op_sel_hi:[0,1,1]
	v_pk_fma_f32 v[12:13], v[226:227], v[110:111], v[12:13] op_sel_hi:[0,1,1]
	v_pk_fma_f32 v[10:11], v[226:227], v[112:113], v[10:11] op_sel_hi:[0,1,1]
	v_pk_fma_f32 v[6:7], v[226:227], v[114:115], v[6:7] op_sel_hi:[0,1,1]
	v_pk_fma_f32 v[4:5], v[226:227], v[116:117], v[4:5] op_sel_hi:[0,1,1]
	v_pk_fma_f32 v[2:3], v[226:227], v[118:119], v[2:3] op_sel_hi:[0,1,1]
	v_pk_fma_f32 v[0:1], v[226:227], v[120:121], v[0:1] op_sel_hi:[0,1,1]
	s_waitcnt vmcnt(0) lgkmcnt(0)
	v_pk_fma_f32 v[74:75], v[226:227], v[228:229], v[74:75] op_sel:[1,0,0] op_sel_hi:[1,1,1]
	v_pk_fma_f32 v[14:15], v[226:227], v[230:231], v[14:15] op_sel:[1,0,0] op_sel_hi:[1,1,1]
	v_pk_fma_f32 v[12:13], v[226:227], v[232:233], v[12:13] op_sel:[1,0,0] op_sel_hi:[1,1,1]
	v_pk_fma_f32 v[10:11], v[226:227], v[234:235], v[10:11] op_sel:[1,0,0] op_sel_hi:[1,1,1]
	v_pk_fma_f32 v[6:7], v[226:227], v[236:237], v[6:7] op_sel:[1,0,0] op_sel_hi:[1,1,1]
	v_pk_fma_f32 v[4:5], v[226:227], v[238:239], v[4:5] op_sel:[1,0,0] op_sel_hi:[1,1,1]
	v_pk_fma_f32 v[2:3], v[226:227], v[240:241], v[2:3] op_sel:[1,0,0] op_sel_hi:[1,1,1]
	v_pk_fma_f32 v[0:1], v[226:227], v[242:243], v[0:1] op_sel:[1,0,0] op_sel_hi:[1,1,1]
	s_addk_i32 s1, 0x1000
	s_addk_i32 s0, 0x200
	s_cmpk_lg_u32 s1, 0x8000
	s_cbranch_scc1 .LBB0_412

; DEVI float bf2f(bf16_t b) { return __uint_as_float(((unsigned)b) << 16); }
; DEVI bf16_t f2bf(float f) { return (bf16_t)cvt_pk_bf16(f, 0.f); }
; DEVI float sigmoidf_(float x) { return __builtin_amdgcn_rcpf(1.0f + __expf(-x)); }
; DEVI void rwkv_prep(const Params& p, int l, unsigned char* smem, int item) {
;     ...
;     bf16_t xrr[17], xkr[17], vfr[16];
;     xrr[0] = tok0 > 0 ? P[(size_t)(tok0 - 1) * 2048 + c] : (bf16_t)0; xkr[0] = tok0 > 0 ? P[(size_t)(tok0 - 1) * 2048 + 512 + c] : (bf16_t)0;
; #pragma unroll
;     for (int t = 0; t < 16; ++t) { xrr[t + 1] = P[(size_t)(tok0 + t) * 2048 + c]; xkr[t + 1] = P[(size_t)(tok0 + t) * 2048 + 512 + c]; vfr[t] = l > 0 ? VF[(size_t)(tok0 + t) * 512 + c] : (bf16_t)0; }
; #pragma unroll
;     for (int t = 0; t < 16; ++t) {
;         const size_t tok = tok0 + t;
;         const float xr = bf2f(xrr[t + 1]), xk = bf2f(xkr[t + 1]), xpr = bf2f(xrr[t]), xpk = bf2f(xkr[t]);
;         const float r = xr + (xpr - xr) * mu_r, k = xk + (xpk - xk) * mu_k;
;         float v = sVx[c * 16 + t];
;         const float z = -(w0 + wacc[t]);
;         const float sp = fmaxf(z, 0.f) + __logf(1.0f + __expf(-fabsf(z)));
;         const float decay = __expf(-__expf(-sp - 0.5f));
;         const float a = sigmoidf_(a0 + aacc[t]);
;         if (l == 0) VF[tok * 512 + c] = f2bf(v);
;         else { const float vf = bf2f(vfr[t]); v = v + (vf - v) * sigmoidf_(v0 + vacc[t]); }
.LBB0_417:
	global_load_ushort v130, v[62:63], off
	global_load_ushort v129, v[62:63], off offset:1024
	v_lshl_add_u64 v[8:9], v[16:17], 1, s[30:31]
	s_mov_b64 s[0:1], 0x38f40000
	v_lshl_add_u64 v[8:9], v[8:9], 0, s[0:1]
	v_mov_b32_e32 v126, 0
	s_and_b64 vcc, exec, s[6:7]
	v_mov_b32_e32 v131, 0
	v_mov_b32_e32 v220, 0
	s_cbranch_vccnz .LBB0_419
	s_lshl_b64 s[0:1], s[28:29], 10
	v_lshl_add_u64 v[62:63], v[8:9], 0, s[0:1]
	global_load_ushort v220, v[62:63], off
.LBB0_419:
	global_load_ushort v124, v[60:61], off
	global_load_ushort v125, v[60:61], off offset:1024
	s_and_b64 vcc, exec, s[6:7]
	v_mov_b32_e32 v221, 0
	s_cbranch_vccnz .LBB0_421
	s_lshl_b64 s[0:1], s[88:89], 10
	v_lshl_add_u64 v[60:61], v[8:9], 0, s[0:1]
	global_load_ushort v221, v[60:61], off
.LBB0_421:
	global_load_ushort v121, v[58:59], off
	global_load_ushort v122, v[58:59], off offset:1024
	v_mov_b32_e32 v120, 0
	s_and_b64 vcc, exec, s[6:7]
	v_mov_b32_e32 v123, 0
	v_mov_b32_e32 v222, 0
	s_cbranch_vccnz .LBB0_423
	s_lshl_b64 s[0:1], s[82:83], 10
	v_lshl_add_u64 v[58:59], v[8:9], 0, s[0:1]
	global_load_ushort v222, v[58:59], off
.LBB0_423:
	global_load_ushort v118, v[56:57], off
	global_load_ushort v119, v[56:57], off offset:1024
	s_and_b64 vcc, exec, s[6:7]
	v_mov_b32_e32 v223, 0
	s_cbranch_vccnz .LBB0_425
	s_lshl_b64 s[0:1], s[96:97], 10
	v_lshl_add_u64 v[56:57], v[8:9], 0, s[0:1]
	global_load_ushort v223, v[56:57], off
.LBB0_425:
	global_load_ushort v115, v[54:55], off
	global_load_ushort v116, v[54:55], off offset:1024
	v_mov_b32_e32 v114, 0
	s_and_b64 vcc, exec, s[6:7]
	v_mov_b32_e32 v117, 0
	v_mov_b32_e32 v224, 0
	s_cbranch_vccnz .LBB0_427
	s_lshl_b64 s[0:1], s[94:95], 10
	v_lshl_add_u64 v[54:55], v[8:9], 0, s[0:1]
	global_load_ushort v224, v[54:55], off
.LBB0_427:
	global_load_ushort v112, v[52:53], off
	global_load_ushort v113, v[52:53], off offset:1024
	s_and_b64 vcc, exec, s[6:7]
	v_mov_b32_e32 v225, 0
	s_cbranch_vccnz .LBB0_429
	s_lshl_b64 s[0:1], s[50:51], 10
	v_lshl_add_u64 v[52:53], v[8:9], 0, s[0:1]
	global_load_ushort v225, v[52:53], off
.LBB0_429:
	global_load_ushort v109, v[50:51], off
	global_load_ushort v110, v[50:51], off offset:1024
	v_mov_b32_e32 v108, 0
	s_and_b64 vcc, exec, s[6:7]
	v_mov_b32_e32 v111, 0
	v_mov_b32_e32 v226, 0
	s_cbranch_vccnz .LBB0_431
	s_lshl_b64 s[0:1], s[48:49], 10
	v_lshl_add_u64 v[50:51], v[8:9], 0, s[0:1]
	global_load_ushort v226, v[50:51], off
.LBB0_431:
	global_load_ushort v62, v[48:49], off
	global_load_ushort v63, v[48:49], off offset:1024
	s_and_b64 vcc, exec, s[6:7]
	v_mov_b32_e32 v227, 0
	s_cbranch_vccnz .LBB0_433
	s_lshl_b64 s[0:1], s[46:47], 10
	v_lshl_add_u64 v[48:49], v[8:9], 0, s[0:1]
	global_load_ushort v227, v[48:49], off
.LBB0_433:
	global_load_ushort v59, v[46:47], off
	global_load_ushort v60, v[46:47], off offset:1024
	v_mov_b32_e32 v58, 0
	s_and_b64 vcc, exec, s[6:7]
	v_mov_b32_e32 v61, 0
	v_mov_b32_e32 v228, 0
	s_cbranch_vccnz .LBB0_435
	s_lshl_b64 s[0:1], s[44:45], 10
	v_lshl_add_u64 v[46:47], v[8:9], 0, s[0:1]
	global_load_ushort v228, v[46:47], off
.LBB0_435:
	global_load_ushort v56, v[42:43], off
	global_load_ushort v57, v[42:43], off offset:1024
	s_and_b64 vcc, exec, s[6:7]
	v_mov_b32_e32 v229, 0
	s_cbranch_vccnz .LBB0_437
	s_lshl_b64 s[0:1], s[42:43], 10
	v_lshl_add_u64 v[42:43], v[8:9], 0, s[0:1]
	global_load_ushort v229, v[42:43], off
.LBB0_437:
	global_load_ushort v53, v[40:41], off
	global_load_ushort v54, v[40:41], off offset:1024
	v_mov_b32_e32 v52, 0
	s_and_b64 vcc, exec, s[6:7]
	v_mov_b32_e32 v55, 0
	v_mov_b32_e32 v230, 0
	s_cbranch_vccnz .LBB0_439
	s_lshl_b64 s[0:1], s[40:41], 10
	v_lshl_add_u64 v[40:41], v[8:9], 0, s[0:1]
	global_load_ushort v230, v[40:41], off
.LBB0_439:
	global_load_ushort v50, v[38:39], off
	global_load_ushort v51, v[38:39], off offset:1024
	s_and_b64 vcc, exec, s[6:7]
	v_mov_b32_e32 v231, 0
	s_cbranch_vccnz .LBB0_441
	s_lshl_b64 s[0:1], s[36:37], 10
	v_lshl_add_u64 v[38:39], v[8:9], 0, s[0:1]
	global_load_ushort v231, v[38:39], off
.LBB0_441:
	global_load_ushort v47, v[36:37], off
	global_load_ushort v48, v[36:37], off offset:1024
	v_mov_b32_e32 v46, 0
	s_and_b64 vcc, exec, s[6:7]
	v_mov_b32_e32 v49, 0
	v_mov_b32_e32 v232, 0
	s_cbranch_vccnz .LBB0_443
	s_lshl_b64 s[0:1], s[34:35], 10
	v_lshl_add_u64 v[36:37], v[8:9], 0, s[0:1]
	global_load_ushort v232, v[36:37], off
.LBB0_443:
	global_load_ushort v42, v[34:35], off
	global_load_ushort v43, v[34:35], off offset:1024
	s_and_b64 vcc, exec, s[6:7]
	v_mov_b32_e32 v233, 0
	s_cbranch_vccnz .LBB0_445
	s_lshl_b64 s[0:1], s[26:27], 10
	v_lshl_add_u64 v[34:35], v[8:9], 0, s[0:1]
	global_load_ushort v233, v[34:35], off
.LBB0_445:
	global_load_ushort v39, v[32:33], off
	global_load_ushort v40, v[32:33], off offset:1024
	v_mov_b32_e32 v36, 0
	s_and_b64 vcc, exec, s[6:7]
	v_mov_b32_e32 v41, 0
	v_mov_b32_e32 v234, 0
	s_cbranch_vccnz .LBB0_447
	s_lshl_b64 s[0:1], s[24:25], 10
	v_lshl_add_u64 v[32:33], v[8:9], 0, s[0:1]
	global_load_ushort v234, v[32:33], off
.LBB0_447:
	global_load_ushort v32, v[30:31], off
	s_nop 0
	global_load_ushort v30, v[30:31], off offset:1024
	s_and_b64 vcc, exec, s[6:7]
	v_mov_b32_e32 v235, 0
	s_cbranch_vccnz .LBB0_449
	s_lshl_b64 s[0:1], s[78:79], 10
	v_lshl_add_u64 v[34:35], v[8:9], 0, s[0:1]
	global_load_ushort v235, v[34:35], off
.LBB0_449:
	s_waitcnt vmcnt(0)
	v_lshlrev_b32_e32 v131, 16, v220
	v_lshlrev_b32_e32 v126, 16, v221
	v_lshlrev_b32_e32 v123, 16, v222
	v_lshlrev_b32_e32 v120, 16, v223
	v_lshlrev_b32_e32 v117, 16, v224
	v_lshlrev_b32_e32 v114, 16, v225
	v_lshlrev_b32_e32 v111, 16, v226
	v_lshlrev_b32_e32 v108, 16, v227
	v_lshlrev_b32_e32 v61, 16, v228
	v_lshlrev_b32_e32 v58, 16, v229
	v_lshlrev_b32_e32 v55, 16, v230
	v_lshlrev_b32_e32 v52, 16, v231
	v_lshlrev_b32_e32 v49, 16, v232
	v_lshlrev_b32_e32 v46, 16, v233
	v_lshlrev_b32_e32 v41, 16, v234
	v_lshlrev_b32_e32 v36, 16, v235
	ds_read_b32 v31, v83 offset:16384
	v_readlane_b32 s2, v253, 50
	v_readlane_b32 s3, v253, 51
	s_mov_b64 s[0:1], -1
	s_and_b64 vcc, exec, s[2:3]
	s_cbranch_vccz .LBB0_451
	s_waitcnt vmcnt(32)
	v_add_f32_e32 v33, v74, v107
	v_mul_f32_e32 v33, 0xbfb8aa3b, v33
	v_exp_f32_e32 v33, v33
	s_waitcnt lgkmcnt(0)
	v_sub_f32_e32 v34, v131, v31
	v_add_f32_e32 v33, 1.0, v33
	v_rcp_f32_e32 v33, v33
	s_nop 0
	v_fma_f32 v33, v33, v34, v31
	v_cvt_pk_bf16_f32 v132, v33, s0
	s_mov_b64 s[0:1], 0
